# K-serpentine: odd units of each WG traverse K-tile pairs in reverse (L2 reuse of A panel) in FFN1-in, FFN2-in, mix-in GEMMs
# speedup vs baseline: 1.0016x; 1.0008x over previous
.LBB0_169:
	s_add_u32 s16, s4, 0xc000000
	s_mov_b64 s[18:19], 0x80
	s_addc_u32 s17, s5, 0
	v_lshl_add_u64 v[4:5], v[0:1], 0, s[18:19]
	s_add_i32 m0, s39, 0x18000
	s_mov_b64 s[20:21], 0x20080
	s_waitcnt vmcnt(2)
	s_barrier
	global_load_lds_dwordx4 v[4:5], off
	v_lshl_add_u64 v[4:5], v[0:1], 0, s[20:21]
	s_add_i32 m0, s39, 0x1a000
	s_add_i32 s60, s39, 0x8000
	global_load_lds_dwordx4 v[4:5], off
	v_lshl_add_u64 v[4:5], v[2:3], 0, s[18:19]
	s_mov_b32 m0, s60
	s_add_i32 s61, s39, 0xa000
	global_load_lds_dwordx4 v[4:5], off
	v_lshl_add_u64 v[2:3], v[2:3], 0, s[20:21]
	s_mov_b32 m0, s61
	s_mov_b64 s[22:23], 0x40080
	global_load_lds_dwordx4 v[2:3], off
	v_lshl_add_u64 v[2:3], v[0:1], 0, s[22:23]
	s_add_i32 m0, s39, 0x1c000
	s_mov_b64 s[24:25], 0x60080
	global_load_lds_dwordx4 v[2:3], off
	v_lshl_add_u64 v[0:1], v[0:1], 0, s[24:25]
	s_add_i32 m0, s39, 0x1e000
	s_movk_i32 s5, 0x3c0
	global_load_lds_dwordx4 v[0:1], off
	v_and_b32_e32 v0, 48, v139
	v_lshlrev_b32_e32 v1, 6, v139
	v_and_or_b32 v0, v1, s5, v0
	v_lshlrev_b32_e32 v1, 2, v139
	s_lshl_b32 s4, s29, 13
	v_and_b32_e32 v1, 32, v1
	v_bitop3_b32 v2, v0, s4, v1 bitop3:0xde
	s_lshl_b32 s4, s28, 5
	s_and_b32 s63, s4, 0x60
	s_lshl_b32 s62, s29, 6
	s_lshl_b32 s4, s63, 7
	s_cmpk_lt_u32 s27, 0x100
	s_sext_i32_i16 s73, s26
	v_bitop3_b32 v140, s4, v0, v1 bitop3:0xf6
	s_waitcnt vmcnt(0)
	s_cselect_b64 s[26:27], -1, 0
	s_add_i32 s68, 0, 0x10000
	s_add_i32 s70, 0, 0x14000
	v_add_u32_e32 v141, s68, v140
	v_add_u32_e32 v142, s70, v140
	s_add_i32 s68, s68, s53
	s_add_i32 s70, s70, s53
	s_add_i32 s72, 0, 0x18000
	s_ashr_i32 s64, s46, 31
	v_mov_b64_e32 v[132:133], 0x1600
	v_mov_b64_e32 v[134:135], 0x15ff
	v_add_u32_e32 v143, 0, v2
	s_movk_i32 s65, 0x1600
	s_add_i32 s66, s39, 0xc000
	s_add_i32 s67, s39, 0xe000
	s_add_i32 s69, s68, 0x2000
	s_add_i32 s71, s70, 0x2000
	v_add_u32_e32 v144, s72, v140
	s_barrier
	s_mov_b32 s98, -1
	s_branch .LBB0_172

.LBB0_172:
	s_not_b32 s98, s98
	s_and_b32 s100, s98, 14
	s_and_b32 s99, s98, 0x200
	s_sub_i32 s99, 0x100, s99
	s_andn2_b32 s101, 0x700, s98
	s_add_i32 s59, s59, 1
	s_mul_i32 s4, s59, s64
	s_mul_hi_u32 s5, s59, s46
	s_add_i32 s5, s5, s4
	s_mul_i32 s4, s59, s46
	s_add_u32 s34, s4, s47
	s_addc_u32 s35, s5, s54
	v_cmp_gt_i64_e32 vcc, s[34:35], v[134:135]
	v_cmp_lt_i64_e64 s[4:5], s[34:35], v[132:133]
	s_cbranch_vccnz .LBB0_174
	s_ashr_i32 s28, s34, 31
	s_lshr_b32 s28, s28, 29
	s_add_i32 s28, s34, s28
	s_ashr_i32 s29, s28, 3
	s_and_b32 s28, s28, -8
	s_sub_i32 s28, s34, s28
	s_cmp_lt_i32 s28, 0
	s_cselect_b32 s30, s55, 0x2c0
	s_mul_i32 s28, s28, s30
	s_add_i32 s28, s28, s29
	s_mul_hi_i32 s29, s28, 0x2e8ba2e9
	s_lshr_b32 s30, s29, 31
	s_ashr_i32 s29, s29, 5
	s_add_i32 s29, s29, s30
	s_lshl_b32 s30, s29, 3
	s_sub_i32 s31, 0x100, s30
	s_min_i32 s31, s31, 8
	s_abs_i32 s34, s31
	v_cvt_f32_u32_e32 v0, s34
	s_sub_i32 s36, 0, s34
	s_mulk_i32 s29, 0xb0
	s_sub_i32 s29, s28, s29
	v_rcp_iflag_f32_e32 v0, v0
	s_abs_i32 s28, s29
	s_xor_b32 s35, s29, s31
	s_ashr_i32 s35, s35, 31
	v_mul_f32_e32 v0, 0x4f7ffffe, v0
	v_cvt_u32_f32_e32 v0, v0
	s_nop 0
	v_readfirstlane_b32 s37, v0
	s_mul_i32 s36, s36, s37
	s_mul_hi_u32 s36, s37, s36
	s_add_i32 s37, s37, s36
	s_mul_hi_u32 s36, s28, s37
	s_mul_i32 s37, s36, s34
	s_sub_i32 s28, s28, s37
	s_add_i32 s44, s36, 1
	s_sub_i32 s37, s28, s34
	s_cmp_ge_u32 s28, s34
	s_cselect_b32 s36, s44, s36
	s_cselect_b32 s28, s37, s28
	s_add_i32 s37, s36, 1
	s_cmp_ge_u32 s28, s34
	s_cselect_b32 s28, s37, s36
	s_xor_b32 s28, s28, s35
	s_sub_i32 s28, s28, s35
	s_mul_i32 s31, s28, s31
	s_sub_i32 s29, s29, s31
	s_add_i32 s30, s30, s29
.LBB0_174:
	s_ashr_i32 s31, s30, 31
	s_lshl_b64 s[34:35], s[30:31], 19
	s_add_u32 s34, s48, s34
	s_addc_u32 s35, s49, s35
	s_ashr_i32 s29, s28, 31
	s_lshl_b64 s[36:37], s[28:29], 19
	s_add_u32 s36, s51, s36
	s_mov_b32 s44, s100
	s_addc_u32 s37, s52, s37
	s_ashr_i32 s45, s44, 31
	s_lshl_b64 s[76:77], s[44:45], 7
	s_add_i32 s78, s76, s99
	s_mov_b32 s79, 0
	s_add_u32 s44, s42, s78
	ds_read_b128 v[0:3], v141
	ds_read_b128 v[4:7], v141 offset:1024
	ds_read_b128 v[8:11], v141 offset:2048
	ds_read_b128 v[12:15], v141 offset:3072
	ds_read_b128 v[16:19], v142
	ds_read_b128 v[20:23], v142 offset:1024
	ds_read_b128 v[24:27], v142 offset:2048
	ds_read_b128 v[28:31], v142 offset:3072
	s_addc_u32 s45, s43, s79
	s_and_b64 s[74:75], s[4:5], exec
	s_cselect_b32 s31, s37, s41
	s_cselect_b32 s74, s36, s40
	s_add_u32 s78, s40, s78
	s_addc_u32 s79, s41, s79
	s_add_u32 s76, s42, s76
	s_mov_b32 s29, 0
	s_addc_u32 s77, s43, s77
	v_lshl_add_u64 v[64:65], s[76:77], 0, v[130:131]
	s_mov_b32 m0, s66
	v_lshl_add_u64 v[66:67], v[64:65], 0, s[22:23]
	ds_read_b128 v[32:35], v143
	ds_read_b128 v[36:39], v143 offset:1024
	ds_read_b128 v[40:43], v143 offset:2048
	ds_read_b128 v[44:47], v143 offset:3072
	ds_read_b128 v[48:51], v143 offset:4096
	ds_read_b128 v[52:55], v143 offset:5120
	ds_read_b128 v[56:59], v143 offset:6144
	ds_read_b128 v[60:63], v143 offset:7168
	global_load_lds_dwordx4 v[66:67], off
	v_lshl_add_u64 v[64:65], v[64:65], 0, s[24:25]
	s_mov_b32 m0, s67
	s_and_b64 s[76:77], s[4:5], exec
	global_load_lds_dwordx4 v[64:65], off
	s_waitcnt vmcnt(16)
	s_waitcnt lgkmcnt(0)
	s_cselect_b32 s75, s35, s43
	s_cselect_b32 s76, s34, s42
	s_add_u32 s74, s74, s101
	s_addc_u32 s31, s31, 0
	s_add_u32 s76, s76, s101
	s_addc_u32 s75, s75, 0
	s_barrier
	s_waitcnt lgkmcnt(0)
	v_mfma_f32_16x16x32_bf16 v[64:67], v[0:3], v[32:35], 0
	v_mfma_f32_16x16x32_bf16 v[68:71], v[8:11], v[32:35], 0
	v_mfma_f32_16x16x32_bf16 v[72:75], v[0:3], v[40:43], 0
	v_mfma_f32_16x16x32_bf16 v[76:79], v[8:11], v[40:43], 0
	v_mfma_f32_16x16x32_bf16 v[80:83], v[0:3], v[48:51], 0
	v_mfma_f32_16x16x32_bf16 v[84:87], v[8:11], v[48:51], 0
	v_mfma_f32_16x16x32_bf16 v[88:91], v[0:3], v[56:59], 0
	v_mfma_f32_16x16x32_bf16 v[92:95], v[8:11], v[56:59], 0
	v_mfma_f32_16x16x32_bf16 v[64:67], v[4:7], v[36:39], v[64:67]
	v_mfma_f32_16x16x32_bf16 v[68:71], v[12:15], v[36:39], v[68:71]
	v_mfma_f32_16x16x32_bf16 v[72:75], v[4:7], v[44:47], v[72:75]
	v_mfma_f32_16x16x32_bf16 v[76:79], v[12:15], v[44:47], v[76:79]
	v_mfma_f32_16x16x32_bf16 v[80:83], v[4:7], v[52:55], v[80:83]
	v_mfma_f32_16x16x32_bf16 v[84:87], v[12:15], v[52:55], v[84:87]
	v_mfma_f32_16x16x32_bf16 v[88:91], v[4:7], v[60:63], v[88:91]
	v_mfma_f32_16x16x32_bf16 v[100:103], v[12:15], v[60:63], v[92:95]
	v_mfma_f32_16x16x32_bf16 v[92:95], v[16:19], v[32:35], 0
	v_mfma_f32_16x16x32_bf16 v[32:35], v[24:27], v[32:35], 0
	v_mfma_f32_16x16x32_bf16 v[104:107], v[20:23], v[36:39], v[92:95]
	v_mfma_f32_16x16x32_bf16 v[32:35], v[28:31], v[36:39], v[32:35]
	v_mfma_f32_16x16x32_bf16 v[36:39], v[16:19], v[40:43], 0
	v_mfma_f32_16x16x32_bf16 v[40:43], v[24:27], v[40:43], 0
	v_mfma_f32_16x16x32_bf16 v[36:39], v[20:23], v[44:47], v[36:39]
	v_mfma_f32_16x16x32_bf16 v[40:43], v[28:31], v[44:47], v[40:43]
	v_mfma_f32_16x16x32_bf16 v[44:47], v[16:19], v[48:51], 0
	v_mfma_f32_16x16x32_bf16 v[48:51], v[24:27], v[48:51], 0
	v_mfma_f32_16x16x32_bf16 v[44:47], v[20:23], v[52:55], v[44:47]
	v_mfma_f32_16x16x32_bf16 v[48:51], v[28:31], v[52:55], v[48:51]
	v_mfma_f32_16x16x32_bf16 v[52:55], v[16:19], v[56:59], 0
	v_mfma_f32_16x16x32_bf16 v[56:59], v[24:27], v[56:59], 0
	v_mfma_f32_16x16x32_bf16 v[52:55], v[20:23], v[60:63], v[52:55]
	v_mfma_f32_16x16x32_bf16 v[56:59], v[28:31], v[60:63], v[56:59]
	s_barrier
	s_mov_b32 m0, s68
	v_lshl_add_u64 v[244:245], s[78:79], 0, v[128:129]
	global_load_lds_dwordx4 v[244:245], off
	v_lshl_add_u64 v[136:137], v[244:245], 0, s[0:1]
	s_mov_b32 m0, s69
	v_lshl_add_u64 v[246:247], s[44:45], 0, v[130:131]
	global_load_lds_dwordx4 v[136:137], off
	v_lshl_add_u64 v[136:137], v[244:245], 0, s[2:3]
	s_mov_b32 m0, s70
	s_nop 0
	global_load_lds_dwordx4 v[136:137], off
	v_lshl_add_u64 v[136:137], v[244:245], 0, s[8:9]
	s_mov_b32 m0, s71
	s_nop 0
	global_load_lds_dwordx4 v[136:137], off
	s_mov_b32 m0, s39
	v_lshl_add_u64 v[136:137], v[246:247], 0, s[0:1]
	global_load_lds_dwordx4 v[246:247], off
	s_mov_b32 m0, s56
	s_nop 0
	global_load_lds_dwordx4 v[136:137], off
	ds_read_b128 v[60:63], v143 offset:16384
	ds_read_b128 v[92:95], v143 offset:17408
	ds_read_b128 v[96:99], v143 offset:18432
	ds_read_b128 v[108:111], v143 offset:19456
	ds_read_b128 v[112:115], v143 offset:20480
	ds_read_b128 v[116:119], v143 offset:21504
	ds_read_b128 v[120:123], v143 offset:22528
	ds_read_b128 v[124:127], v143 offset:23552
	s_waitcnt vmcnt(16)
	s_waitcnt lgkmcnt(0)
	s_barrier
	s_waitcnt lgkmcnt(0)
	v_mfma_f32_16x16x32_bf16 v[146:149], v[0:3], v[60:63], 0
	v_mfma_f32_16x16x32_bf16 v[154:157], v[0:3], v[96:99], 0
	v_mfma_f32_16x16x32_bf16 v[162:165], v[0:3], v[112:115], 0
	v_mfma_f32_16x16x32_bf16 v[0:3], v[0:3], v[120:123], 0
	v_mfma_f32_16x16x32_bf16 v[146:149], v[4:7], v[92:95], v[146:149]
	v_mfma_f32_16x16x32_bf16 v[154:157], v[4:7], v[108:111], v[154:157]
	v_mfma_f32_16x16x32_bf16 v[162:165], v[4:7], v[116:119], v[162:165]
	v_mfma_f32_16x16x32_bf16 v[0:3], v[4:7], v[124:127], v[0:3]
	v_mfma_f32_16x16x32_bf16 v[4:7], v[8:11], v[120:123], 0
	v_mfma_f32_16x16x32_bf16 v[150:153], v[8:11], v[60:63], 0
	v_mfma_f32_16x16x32_bf16 v[158:161], v[8:11], v[96:99], 0
	v_mfma_f32_16x16x32_bf16 v[166:169], v[8:11], v[112:115], 0
	v_mfma_f32_16x16x32_bf16 v[4:7], v[12:15], v[124:127], v[4:7]
	v_mfma_f32_16x16x32_bf16 v[150:153], v[12:15], v[92:95], v[150:153]
	v_mfma_f32_16x16x32_bf16 v[158:161], v[12:15], v[108:111], v[158:161]
	v_mfma_f32_16x16x32_bf16 v[166:169], v[12:15], v[116:119], v[166:169]
	v_mfma_f32_16x16x32_bf16 v[12:15], v[24:27], v[60:63], 0
	v_mfma_f32_16x16x32_bf16 v[170:173], v[28:31], v[92:95], v[12:15]
	v_mfma_f32_16x16x32_bf16 v[12:15], v[16:19], v[96:99], 0
	v_mfma_f32_16x16x32_bf16 v[174:177], v[20:23], v[108:111], v[12:15]
	v_mfma_f32_16x16x32_bf16 v[12:15], v[24:27], v[96:99], 0
	v_mfma_f32_16x16x32_bf16 v[178:181], v[28:31], v[108:111], v[12:15]
	v_mfma_f32_16x16x32_bf16 v[12:15], v[16:19], v[112:115], 0
	v_mfma_f32_16x16x32_bf16 v[182:185], v[20:23], v[116:119], v[12:15]
	v_mfma_f32_16x16x32_bf16 v[12:15], v[24:27], v[112:115], 0
	v_mfma_f32_16x16x32_bf16 v[8:11], v[16:19], v[60:63], 0
	v_mfma_f32_16x16x32_bf16 v[186:189], v[28:31], v[116:119], v[12:15]
	v_mfma_f32_16x16x32_bf16 v[12:15], v[16:19], v[120:123], 0
	v_mfma_f32_16x16x32_bf16 v[8:11], v[20:23], v[92:95], v[8:11]
	v_mfma_f32_16x16x32_bf16 v[190:193], v[20:23], v[124:127], v[12:15]
	v_mfma_f32_16x16x32_bf16 v[12:15], v[24:27], v[120:123], 0
	v_mfma_f32_16x16x32_bf16 v[194:197], v[28:31], v[124:127], v[12:15]
	s_barrier
	s_add_i32 s79, 0, 0x1c000
	v_add_u32_e32 v136, s79, v140
	s_nop 2
	s_mov_b32 m0, s57
	v_lshl_add_u64 v[92:93], v[246:247], 0, s[2:3]
	global_load_lds_dwordx4 v[92:93], off
	v_lshl_add_u64 v[92:93], v[246:247], 0, s[8:9]
	s_mov_b32 m0, s58
	s_nop 0
	global_load_lds_dwordx4 v[92:93], off
	ds_read_b128 v[12:15], v144
	ds_read_b128 v[20:23], v144 offset:1024
	ds_read_b128 v[24:27], v144 offset:2048
	ds_read_b128 v[198:201], v144 offset:3072
	ds_read_b128 v[202:205], v136
	ds_read_b128 v[206:209], v136 offset:1024
	ds_read_b128 v[212:215], v136 offset:2048
	ds_read_b128 v[216:219], v136 offset:3072
	ds_read_b128 v[16:19], v143 offset:32768
	ds_read_b128 v[28:31], v143 offset:33792
	ds_read_b128 v[60:63], v143 offset:34816
	ds_read_b128 v[220:223], v143 offset:35840
	ds_read_b128 v[224:227], v143 offset:36864
	ds_read_b128 v[228:231], v143 offset:37888
	ds_read_b128 v[232:235], v143 offset:38912
	ds_read_b128 v[236:239], v143 offset:39936
	s_waitcnt vmcnt(8)
	s_waitcnt lgkmcnt(0)
	s_barrier
	s_waitcnt lgkmcnt(0)
	v_mfma_f32_16x16x32_bf16 v[64:67], v[12:15], v[16:19], v[64:67]
	v_mfma_f32_16x16x32_bf16 v[124:127], v[20:23], v[28:31], v[64:67]
	v_mfma_f32_16x16x32_bf16 v[64:67], v[24:27], v[16:19], v[68:71]
	v_mfma_f32_16x16x32_bf16 v[112:115], v[198:201], v[28:31], v[64:67]
	v_mfma_f32_16x16x32_bf16 v[64:67], v[12:15], v[60:63], v[72:75]
	v_mfma_f32_16x16x32_bf16 v[108:111], v[20:23], v[220:223], v[64:67]
	v_mfma_f32_16x16x32_bf16 v[64:67], v[24:27], v[60:63], v[76:79]
	v_mfma_f32_16x16x32_bf16 v[96:99], v[198:201], v[220:223], v[64:67]
	v_mfma_f32_16x16x32_bf16 v[64:67], v[12:15], v[224:227], v[80:83]
	v_mfma_f32_16x16x32_bf16 v[92:95], v[20:23], v[228:231], v[64:67]
	v_mfma_f32_16x16x32_bf16 v[64:67], v[24:27], v[224:227], v[84:87]
	v_mfma_f32_16x16x32_bf16 v[80:83], v[198:201], v[228:231], v[64:67]
	v_mfma_f32_16x16x32_bf16 v[64:67], v[12:15], v[232:235], v[88:91]
	v_mfma_f32_16x16x32_bf16 v[76:79], v[20:23], v[236:239], v[64:67]
	v_mfma_f32_16x16x32_bf16 v[64:67], v[24:27], v[232:235], v[100:103]
	v_mfma_f32_16x16x32_bf16 v[64:67], v[198:201], v[236:239], v[64:67]
	v_mfma_f32_16x16x32_bf16 v[68:71], v[202:205], v[16:19], v[104:107]
	v_mfma_f32_16x16x32_bf16 v[16:19], v[212:215], v[16:19], v[32:35]
	v_mfma_f32_16x16x32_bf16 v[116:119], v[216:219], v[28:31], v[16:19]
	v_mfma_f32_16x16x32_bf16 v[16:19], v[202:205], v[60:63], v[36:39]
	v_mfma_f32_16x16x32_bf16 v[104:107], v[206:209], v[220:223], v[16:19]
	v_mfma_f32_16x16x32_bf16 v[16:19], v[212:215], v[60:63], v[40:43]
	v_mfma_f32_16x16x32_bf16 v[100:103], v[216:219], v[220:223], v[16:19]
	v_mfma_f32_16x16x32_bf16 v[16:19], v[202:205], v[224:227], v[44:47]
	v_mfma_f32_16x16x32_bf16 v[88:91], v[206:209], v[228:231], v[16:19]
	v_mfma_f32_16x16x32_bf16 v[16:19], v[212:215], v[224:227], v[48:51]
	v_mfma_f32_16x16x32_bf16 v[84:87], v[216:219], v[228:231], v[16:19]
	v_mfma_f32_16x16x32_bf16 v[16:19], v[202:205], v[232:235], v[52:55]
	v_mfma_f32_16x16x32_bf16 v[72:75], v[206:209], v[236:239], v[16:19]
	v_mfma_f32_16x16x32_bf16 v[16:19], v[212:215], v[232:235], v[56:59]
	v_mfma_f32_16x16x32_bf16 v[120:123], v[206:209], v[28:31], v[68:71]
	v_mfma_f32_16x16x32_bf16 v[68:71], v[216:219], v[236:239], v[16:19]
	s_barrier
	s_add_i32 s77, s72, s53
	s_nop 2
	v_lshl_add_u64 v[16:17], v[244:245], 0, s[18:19]
	s_mov_b32 m0, s77
	s_add_i32 s78, s77, 0x2000
	global_load_lds_dwordx4 v[16:17], off
	v_lshl_add_u64 v[16:17], v[244:245], 0, s[20:21]
	s_mov_b32 m0, s78
	s_add_i32 s79, s79, s53
	global_load_lds_dwordx4 v[16:17], off
	v_lshl_add_u64 v[16:17], v[244:245], 0, s[22:23]
	s_mov_b32 m0, s79
	s_add_i32 s80, s79, 0x2000
	global_load_lds_dwordx4 v[16:17], off
	v_lshl_add_u64 v[16:17], v[244:245], 0, s[24:25]
	s_mov_b32 m0, s80
	s_nop 0
	global_load_lds_dwordx4 v[16:17], off
	v_lshl_add_u64 v[16:17], v[246:247], 0, s[18:19]
	s_mov_b32 m0, s60
	s_nop 0
	global_load_lds_dwordx4 v[16:17], off
	v_lshl_add_u64 v[16:17], v[246:247], 0, s[20:21]
	s_mov_b32 m0, s61
	s_nop 0
	global_load_lds_dwordx4 v[16:17], off
	ds_read_b128 v[36:39], v143 offset:49152
	ds_read_b128 v[40:43], v143 offset:50176
	ds_read_b128 v[220:223], v143 offset:51200
	ds_read_b128 v[224:227], v143 offset:52224
	ds_read_b128 v[228:231], v143 offset:53248
	ds_read_b128 v[232:235], v143 offset:54272
	ds_read_b128 v[236:239], v143 offset:55296
	ds_read_b128 v[240:243], v143 offset:56320
	s_waitcnt vmcnt(8)
	s_waitcnt lgkmcnt(0)
	s_barrier
	s_waitcnt lgkmcnt(0)
	v_mfma_f32_16x16x32_bf16 v[16:19], v[12:15], v[36:39], v[146:149]
	v_mfma_f32_16x16x32_bf16 v[60:63], v[20:23], v[40:43], v[16:19]
	v_mfma_f32_16x16x32_bf16 v[16:19], v[24:27], v[36:39], v[150:153]
	v_mfma_f32_16x16x32_bf16 v[48:51], v[198:201], v[40:43], v[16:19]
	v_mfma_f32_16x16x32_bf16 v[16:19], v[12:15], v[220:223], v[154:157]
	v_mfma_f32_16x16x32_bf16 v[44:47], v[20:23], v[224:227], v[16:19]
	v_mfma_f32_16x16x32_bf16 v[16:19], v[24:27], v[220:223], v[158:161]
	v_mfma_f32_16x16x32_bf16 v[32:35], v[198:201], v[224:227], v[16:19]
	v_mfma_f32_16x16x32_bf16 v[16:19], v[12:15], v[228:231], v[162:165]
	v_mfma_f32_16x16x32_bf16 v[0:3], v[12:15], v[236:239], v[0:3]
	v_mfma_f32_16x16x32_bf16 v[28:31], v[20:23], v[232:235], v[16:19]
	v_mfma_f32_16x16x32_bf16 v[16:19], v[24:27], v[228:231], v[166:169]
	v_mfma_f32_16x16x32_bf16 v[12:15], v[20:23], v[240:243], v[0:3]
	v_mfma_f32_16x16x32_bf16 v[0:3], v[24:27], v[236:239], v[4:7]
	v_mfma_f32_16x16x32_bf16 v[16:19], v[198:201], v[232:235], v[16:19]
	v_mfma_f32_16x16x32_bf16 v[0:3], v[198:201], v[240:243], v[0:3]
	v_mfma_f32_16x16x32_bf16 v[4:7], v[202:205], v[36:39], v[8:11]
	v_mfma_f32_16x16x32_bf16 v[56:59], v[206:209], v[40:43], v[4:7]
	v_mfma_f32_16x16x32_bf16 v[4:7], v[212:215], v[36:39], v[170:173]
	v_mfma_f32_16x16x32_bf16 v[52:55], v[216:219], v[40:43], v[4:7]
	v_mfma_f32_16x16x32_bf16 v[4:7], v[202:205], v[220:223], v[174:177]
	v_mfma_f32_16x16x32_bf16 v[40:43], v[206:209], v[224:227], v[4:7]
	v_mfma_f32_16x16x32_bf16 v[4:7], v[212:215], v[220:223], v[178:181]
	v_mfma_f32_16x16x32_bf16 v[36:39], v[216:219], v[224:227], v[4:7]
	v_mfma_f32_16x16x32_bf16 v[4:7], v[202:205], v[228:231], v[182:185]
	v_mfma_f32_16x16x32_bf16 v[24:27], v[206:209], v[232:235], v[4:7]
	v_mfma_f32_16x16x32_bf16 v[4:7], v[212:215], v[228:231], v[186:189]
	v_mfma_f32_16x16x32_bf16 v[20:23], v[216:219], v[232:235], v[4:7]
	v_mfma_f32_16x16x32_bf16 v[4:7], v[202:205], v[236:239], v[190:193]
	v_mfma_f32_16x16x32_bf16 v[8:11], v[206:209], v[240:243], v[4:7]
	v_mfma_f32_16x16x32_bf16 v[4:7], v[212:215], v[236:239], v[194:197]
	v_mfma_f32_16x16x32_bf16 v[4:7], v[216:219], v[240:243], v[4:7]
	s_barrier
.LBB0_175:
	s_add_i32 s29, s29, 2
	s_xor_b32 s44, s29, s100
	s_ashr_i32 s45, s44, 31
	s_lshl_b64 s[82:83], s[44:45], 7
	s_add_i32 s45, s82, s99
	s_mov_b32 s81, 0
	s_add_u32 s84, s42, s45
	s_addc_u32 s85, s43, s81
	s_add_u32 s86, s40, s45
	s_addc_u32 s81, s41, s81
	s_cmp_eq_u32 s29, 14
	s_cselect_b32 s45, s75, s85
	s_cselect_b32 s44, s76, s84
	s_cselect_b32 s85, s31, s81
	s_cselect_b32 s84, s74, s86
	s_add_u32 s82, s42, s82
	s_addc_u32 s83, s43, s83
	v_lshl_add_u64 v[212:213], s[82:83], 0, v[130:131]
	s_mov_b32 m0, s66
	v_lshl_add_u64 v[214:215], v[212:213], 0, s[22:23]
	global_load_lds_dwordx4 v[214:215], off
	v_lshl_add_u64 v[212:213], v[212:213], 0, s[24:25]
	s_mov_b32 m0, s67
	s_nop 0
	global_load_lds_dwordx4 v[212:213], off
	ds_read_b128 v[146:149], v141
	ds_read_b128 v[150:153], v141 offset:1024
	ds_read_b128 v[154:157], v141 offset:2048
	ds_read_b128 v[158:161], v141 offset:3072
	ds_read_b128 v[162:165], v142
	ds_read_b128 v[166:169], v142 offset:1024
	ds_read_b128 v[170:173], v142 offset:2048
	ds_read_b128 v[174:177], v142 offset:3072
	ds_read_b128 v[178:181], v143
	ds_read_b128 v[182:185], v143 offset:1024
	ds_read_b128 v[186:189], v143 offset:2048
	ds_read_b128 v[190:193], v143 offset:3072
	ds_read_b128 v[194:197], v143 offset:4096
	ds_read_b128 v[198:201], v143 offset:5120
	ds_read_b128 v[202:205], v143 offset:6144
	ds_read_b128 v[206:209], v143 offset:7168
	s_waitcnt vmcnt(8)
	s_waitcnt lgkmcnt(0)
	s_barrier
	s_waitcnt lgkmcnt(0)
	v_mfma_f32_16x16x32_bf16 v[124:127], v[146:149], v[178:181], v[124:127]
	v_mfma_f32_16x16x32_bf16 v[124:127], v[150:153], v[182:185], v[124:127]
	v_mfma_f32_16x16x32_bf16 v[112:115], v[158:161], v[182:185], v[112:115]
	v_mfma_f32_16x16x32_bf16 v[112:115], v[154:157], v[178:181], v[112:115]
	v_mfma_f32_16x16x32_bf16 v[120:123], v[162:165], v[178:181], v[120:123]
	v_mfma_f32_16x16x32_bf16 v[120:123], v[166:169], v[182:185], v[120:123]
	v_mfma_f32_16x16x32_bf16 v[116:119], v[174:177], v[182:185], v[116:119]
	v_mfma_f32_16x16x32_bf16 v[116:119], v[170:173], v[178:181], v[116:119]
	v_mfma_f32_16x16x32_bf16 v[100:103], v[170:173], v[186:189], v[100:103]
	v_mfma_f32_16x16x32_bf16 v[100:103], v[174:177], v[190:193], v[100:103]
	v_mfma_f32_16x16x32_bf16 v[104:107], v[166:169], v[190:193], v[104:107]
	v_mfma_f32_16x16x32_bf16 v[104:107], v[162:165], v[186:189], v[104:107]
	v_mfma_f32_16x16x32_bf16 v[96:99], v[154:157], v[186:189], v[96:99]
	v_mfma_f32_16x16x32_bf16 v[96:99], v[158:161], v[190:193], v[96:99]
	v_mfma_f32_16x16x32_bf16 v[108:111], v[150:153], v[190:193], v[108:111]
	v_mfma_f32_16x16x32_bf16 v[108:111], v[146:149], v[186:189], v[108:111]
	v_mfma_f32_16x16x32_bf16 v[92:95], v[146:149], v[194:197], v[92:95]
	v_mfma_f32_16x16x32_bf16 v[92:95], v[150:153], v[198:201], v[92:95]
	v_mfma_f32_16x16x32_bf16 v[80:83], v[158:161], v[198:201], v[80:83]
	v_mfma_f32_16x16x32_bf16 v[80:83], v[154:157], v[194:197], v[80:83]
	v_mfma_f32_16x16x32_bf16 v[88:91], v[162:165], v[194:197], v[88:91]
	v_mfma_f32_16x16x32_bf16 v[88:91], v[166:169], v[198:201], v[88:91]
	v_mfma_f32_16x16x32_bf16 v[84:87], v[174:177], v[198:201], v[84:87]
	v_mfma_f32_16x16x32_bf16 v[84:87], v[170:173], v[194:197], v[84:87]
	v_mfma_f32_16x16x32_bf16 v[68:71], v[170:173], v[202:205], v[68:71]
	v_mfma_f32_16x16x32_bf16 v[68:71], v[174:177], v[206:209], v[68:71]
	v_mfma_f32_16x16x32_bf16 v[72:75], v[166:169], v[206:209], v[72:75]
	v_mfma_f32_16x16x32_bf16 v[72:75], v[162:165], v[202:205], v[72:75]
	v_mfma_f32_16x16x32_bf16 v[64:67], v[154:157], v[202:205], v[64:67]
	v_mfma_f32_16x16x32_bf16 v[64:67], v[158:161], v[206:209], v[64:67]
	v_mfma_f32_16x16x32_bf16 v[76:79], v[150:153], v[206:209], v[76:79]
	v_mfma_f32_16x16x32_bf16 v[76:79], v[146:149], v[202:205], v[76:79]
	s_barrier
	s_mov_b32 m0, s68
	v_lshl_add_u64 v[212:213], s[84:85], 0, v[128:129]
	global_load_lds_dwordx4 v[212:213], off
	v_lshl_add_u64 v[214:215], v[212:213], 0, s[0:1]
	s_mov_b32 m0, s69
	s_nop 0
	global_load_lds_dwordx4 v[214:215], off
	v_lshl_add_u64 v[214:215], v[212:213], 0, s[2:3]
	s_mov_b32 m0, s70
	s_nop 0
	global_load_lds_dwordx4 v[214:215], off
	v_lshl_add_u64 v[214:215], v[212:213], 0, s[8:9]
	s_mov_b32 m0, s71
	s_nop 0
	global_load_lds_dwordx4 v[214:215], off
	v_lshl_add_u64 v[214:215], s[44:45], 0, v[130:131]
	s_mov_b32 m0, s39
	v_lshl_add_u64 v[216:217], v[214:215], 0, s[0:1]
	global_load_lds_dwordx4 v[214:215], off
	s_mov_b32 m0, s56
	s_nop 0
	global_load_lds_dwordx4 v[216:217], off
	ds_read_b128 v[178:181], v143 offset:16384
	ds_read_b128 v[182:185], v143 offset:17408
	ds_read_b128 v[186:189], v143 offset:18432
	ds_read_b128 v[190:193], v143 offset:19456
	ds_read_b128 v[194:197], v143 offset:20480
	ds_read_b128 v[198:201], v143 offset:21504
	ds_read_b128 v[202:205], v143 offset:22528
	ds_read_b128 v[206:209], v143 offset:23552
	s_waitcnt vmcnt(8)
	s_waitcnt lgkmcnt(0)
	s_barrier
	s_waitcnt lgkmcnt(0)
	v_mfma_f32_16x16x32_bf16 v[60:63], v[146:149], v[178:181], v[60:63]
	v_mfma_f32_16x16x32_bf16 v[60:63], v[150:153], v[182:185], v[60:63]
	v_mfma_f32_16x16x32_bf16 v[48:51], v[158:161], v[182:185], v[48:51]
	v_mfma_f32_16x16x32_bf16 v[48:51], v[154:157], v[178:181], v[48:51]
	v_mfma_f32_16x16x32_bf16 v[56:59], v[162:165], v[178:181], v[56:59]
	v_mfma_f32_16x16x32_bf16 v[56:59], v[166:169], v[182:185], v[56:59]
	v_mfma_f32_16x16x32_bf16 v[52:55], v[174:177], v[182:185], v[52:55]
	v_mfma_f32_16x16x32_bf16 v[52:55], v[170:173], v[178:181], v[52:55]
	v_mfma_f32_16x16x32_bf16 v[36:39], v[170:173], v[186:189], v[36:39]
	v_mfma_f32_16x16x32_bf16 v[36:39], v[174:177], v[190:193], v[36:39]
	v_mfma_f32_16x16x32_bf16 v[40:43], v[166:169], v[190:193], v[40:43]
	v_mfma_f32_16x16x32_bf16 v[40:43], v[162:165], v[186:189], v[40:43]
	v_mfma_f32_16x16x32_bf16 v[32:35], v[154:157], v[186:189], v[32:35]
	v_mfma_f32_16x16x32_bf16 v[32:35], v[158:161], v[190:193], v[32:35]
	v_mfma_f32_16x16x32_bf16 v[44:47], v[150:153], v[190:193], v[44:47]
	v_mfma_f32_16x16x32_bf16 v[44:47], v[146:149], v[186:189], v[44:47]
	v_mfma_f32_16x16x32_bf16 v[28:31], v[146:149], v[194:197], v[28:31]
	v_mfma_f32_16x16x32_bf16 v[28:31], v[150:153], v[198:201], v[28:31]
	v_mfma_f32_16x16x32_bf16 v[16:19], v[158:161], v[198:201], v[16:19]
	v_mfma_f32_16x16x32_bf16 v[16:19], v[154:157], v[194:197], v[16:19]
	v_mfma_f32_16x16x32_bf16 v[24:27], v[162:165], v[194:197], v[24:27]
	v_mfma_f32_16x16x32_bf16 v[24:27], v[166:169], v[198:201], v[24:27]
	v_mfma_f32_16x16x32_bf16 v[20:23], v[174:177], v[198:201], v[20:23]
	v_mfma_f32_16x16x32_bf16 v[20:23], v[170:173], v[194:197], v[20:23]
	v_mfma_f32_16x16x32_bf16 v[4:7], v[170:173], v[202:205], v[4:7]
	v_mfma_f32_16x16x32_bf16 v[4:7], v[174:177], v[206:209], v[4:7]
	v_mfma_f32_16x16x32_bf16 v[8:11], v[166:169], v[206:209], v[8:11]
	v_mfma_f32_16x16x32_bf16 v[8:11], v[162:165], v[202:205], v[8:11]
	v_mfma_f32_16x16x32_bf16 v[0:3], v[154:157], v[202:205], v[0:3]
	v_mfma_f32_16x16x32_bf16 v[0:3], v[158:161], v[206:209], v[0:3]
	v_mfma_f32_16x16x32_bf16 v[12:15], v[150:153], v[206:209], v[12:15]
	v_mfma_f32_16x16x32_bf16 v[12:15], v[146:149], v[202:205], v[12:15]
	s_barrier
	s_mov_b32 m0, s57
	v_lshl_add_u64 v[216:217], v[214:215], 0, s[2:3]
	global_load_lds_dwordx4 v[216:217], off
	v_lshl_add_u64 v[216:217], v[214:215], 0, s[8:9]
	s_mov_b32 m0, s58
	s_nop 0
	global_load_lds_dwordx4 v[216:217], off
	ds_read_b128 v[146:149], v144
	ds_read_b128 v[150:153], v144 offset:1024
	ds_read_b128 v[154:157], v144 offset:2048
	ds_read_b128 v[158:161], v144 offset:3072
	ds_read_b128 v[162:165], v136
	ds_read_b128 v[166:169], v136 offset:1024
	ds_read_b128 v[170:173], v136 offset:2048
	ds_read_b128 v[174:177], v136 offset:3072
	ds_read_b128 v[178:181], v143 offset:32768
	ds_read_b128 v[182:185], v143 offset:33792
	ds_read_b128 v[186:189], v143 offset:34816
	ds_read_b128 v[190:193], v143 offset:35840
	ds_read_b128 v[194:197], v143 offset:36864
	ds_read_b128 v[198:201], v143 offset:37888
	ds_read_b128 v[202:205], v143 offset:38912
	ds_read_b128 v[206:209], v143 offset:39936
	s_waitcnt vmcnt(8)
	s_waitcnt lgkmcnt(0)
	s_barrier
	s_waitcnt lgkmcnt(0)
	v_mfma_f32_16x16x32_bf16 v[124:127], v[146:149], v[178:181], v[124:127]
	v_mfma_f32_16x16x32_bf16 v[124:127], v[150:153], v[182:185], v[124:127]
	v_mfma_f32_16x16x32_bf16 v[112:115], v[158:161], v[182:185], v[112:115]
	v_mfma_f32_16x16x32_bf16 v[112:115], v[154:157], v[178:181], v[112:115]
	v_mfma_f32_16x16x32_bf16 v[120:123], v[162:165], v[178:181], v[120:123]
	v_mfma_f32_16x16x32_bf16 v[120:123], v[166:169], v[182:185], v[120:123]
	v_mfma_f32_16x16x32_bf16 v[116:119], v[174:177], v[182:185], v[116:119]
	v_mfma_f32_16x16x32_bf16 v[116:119], v[170:173], v[178:181], v[116:119]
	v_mfma_f32_16x16x32_bf16 v[100:103], v[170:173], v[186:189], v[100:103]
	v_mfma_f32_16x16x32_bf16 v[100:103], v[174:177], v[190:193], v[100:103]
	v_mfma_f32_16x16x32_bf16 v[104:107], v[166:169], v[190:193], v[104:107]
	v_mfma_f32_16x16x32_bf16 v[104:107], v[162:165], v[186:189], v[104:107]
	v_mfma_f32_16x16x32_bf16 v[96:99], v[154:157], v[186:189], v[96:99]
	v_mfma_f32_16x16x32_bf16 v[96:99], v[158:161], v[190:193], v[96:99]
	v_mfma_f32_16x16x32_bf16 v[108:111], v[150:153], v[190:193], v[108:111]
	v_mfma_f32_16x16x32_bf16 v[108:111], v[146:149], v[186:189], v[108:111]
	v_mfma_f32_16x16x32_bf16 v[92:95], v[146:149], v[194:197], v[92:95]
	v_mfma_f32_16x16x32_bf16 v[92:95], v[150:153], v[198:201], v[92:95]
	v_mfma_f32_16x16x32_bf16 v[80:83], v[158:161], v[198:201], v[80:83]
	v_mfma_f32_16x16x32_bf16 v[80:83], v[154:157], v[194:197], v[80:83]
	v_mfma_f32_16x16x32_bf16 v[88:91], v[162:165], v[194:197], v[88:91]
	v_mfma_f32_16x16x32_bf16 v[88:91], v[166:169], v[198:201], v[88:91]
	v_mfma_f32_16x16x32_bf16 v[84:87], v[174:177], v[198:201], v[84:87]
	v_mfma_f32_16x16x32_bf16 v[84:87], v[170:173], v[194:197], v[84:87]
	v_mfma_f32_16x16x32_bf16 v[68:71], v[170:173], v[202:205], v[68:71]
	v_mfma_f32_16x16x32_bf16 v[68:71], v[174:177], v[206:209], v[68:71]
	v_mfma_f32_16x16x32_bf16 v[72:75], v[166:169], v[206:209], v[72:75]
	v_mfma_f32_16x16x32_bf16 v[72:75], v[162:165], v[202:205], v[72:75]
	v_mfma_f32_16x16x32_bf16 v[64:67], v[154:157], v[202:205], v[64:67]
	v_mfma_f32_16x16x32_bf16 v[64:67], v[158:161], v[206:209], v[64:67]
	v_mfma_f32_16x16x32_bf16 v[76:79], v[150:153], v[206:209], v[76:79]
	v_mfma_f32_16x16x32_bf16 v[76:79], v[146:149], v[202:205], v[76:79]
	s_barrier
	s_mov_b32 m0, s77
	v_lshl_add_u64 v[216:217], v[212:213], 0, s[18:19]
	global_load_lds_dwordx4 v[216:217], off
	v_lshl_add_u64 v[216:217], v[212:213], 0, s[20:21]
	s_mov_b32 m0, s78
	s_nop 0
	global_load_lds_dwordx4 v[216:217], off
	v_lshl_add_u64 v[216:217], v[212:213], 0, s[22:23]
	s_mov_b32 m0, s79
	v_lshl_add_u64 v[212:213], v[212:213], 0, s[24:25]
	global_load_lds_dwordx4 v[216:217], off
	s_mov_b32 m0, s80
	s_nop 0
	global_load_lds_dwordx4 v[212:213], off
	v_lshl_add_u64 v[212:213], v[214:215], 0, s[18:19]
	s_mov_b32 m0, s60
	s_nop 0
	global_load_lds_dwordx4 v[212:213], off
	v_lshl_add_u64 v[212:213], v[214:215], 0, s[20:21]
	s_mov_b32 m0, s61
	s_nop 0
	global_load_lds_dwordx4 v[212:213], off
	ds_read_b128 v[178:181], v143 offset:49152
	ds_read_b128 v[182:185], v143 offset:50176
	ds_read_b128 v[186:189], v143 offset:51200
	ds_read_b128 v[190:193], v143 offset:52224
	ds_read_b128 v[194:197], v143 offset:53248
	ds_read_b128 v[198:201], v143 offset:54272
	ds_read_b128 v[202:205], v143 offset:55296
	ds_read_b128 v[206:209], v143 offset:56320
	s_waitcnt vmcnt(8)
	s_waitcnt lgkmcnt(0)
	s_barrier
	s_waitcnt lgkmcnt(0)
	v_mfma_f32_16x16x32_bf16 v[60:63], v[146:149], v[178:181], v[60:63]
	v_mfma_f32_16x16x32_bf16 v[60:63], v[150:153], v[182:185], v[60:63]
	v_mfma_f32_16x16x32_bf16 v[48:51], v[158:161], v[182:185], v[48:51]
	v_mfma_f32_16x16x32_bf16 v[48:51], v[154:157], v[178:181], v[48:51]
	v_mfma_f32_16x16x32_bf16 v[56:59], v[162:165], v[178:181], v[56:59]
	v_mfma_f32_16x16x32_bf16 v[56:59], v[166:169], v[182:185], v[56:59]
	v_mfma_f32_16x16x32_bf16 v[52:55], v[174:177], v[182:185], v[52:55]
	v_mfma_f32_16x16x32_bf16 v[52:55], v[170:173], v[178:181], v[52:55]
	v_mfma_f32_16x16x32_bf16 v[36:39], v[170:173], v[186:189], v[36:39]
	v_mfma_f32_16x16x32_bf16 v[36:39], v[174:177], v[190:193], v[36:39]
	v_mfma_f32_16x16x32_bf16 v[40:43], v[166:169], v[190:193], v[40:43]
	v_mfma_f32_16x16x32_bf16 v[40:43], v[162:165], v[186:189], v[40:43]
	v_mfma_f32_16x16x32_bf16 v[32:35], v[154:157], v[186:189], v[32:35]
	v_mfma_f32_16x16x32_bf16 v[32:35], v[158:161], v[190:193], v[32:35]
	v_mfma_f32_16x16x32_bf16 v[44:47], v[150:153], v[190:193], v[44:47]
	v_mfma_f32_16x16x32_bf16 v[44:47], v[146:149], v[186:189], v[44:47]
	v_mfma_f32_16x16x32_bf16 v[28:31], v[146:149], v[194:197], v[28:31]
	v_mfma_f32_16x16x32_bf16 v[28:31], v[150:153], v[198:201], v[28:31]
	v_mfma_f32_16x16x32_bf16 v[16:19], v[158:161], v[198:201], v[16:19]
	v_mfma_f32_16x16x32_bf16 v[16:19], v[154:157], v[194:197], v[16:19]
	v_mfma_f32_16x16x32_bf16 v[24:27], v[162:165], v[194:197], v[24:27]
	v_mfma_f32_16x16x32_bf16 v[24:27], v[166:169], v[198:201], v[24:27]
	v_mfma_f32_16x16x32_bf16 v[20:23], v[174:177], v[198:201], v[20:23]
	v_mfma_f32_16x16x32_bf16 v[20:23], v[170:173], v[194:197], v[20:23]
	v_mfma_f32_16x16x32_bf16 v[4:7], v[170:173], v[202:205], v[4:7]
	v_mfma_f32_16x16x32_bf16 v[4:7], v[174:177], v[206:209], v[4:7]
	v_mfma_f32_16x16x32_bf16 v[8:11], v[166:169], v[206:209], v[8:11]
	v_mfma_f32_16x16x32_bf16 v[8:11], v[162:165], v[202:205], v[8:11]
	v_mfma_f32_16x16x32_bf16 v[0:3], v[154:157], v[202:205], v[0:3]
	v_mfma_f32_16x16x32_bf16 v[0:3], v[158:161], v[206:209], v[0:3]
	v_mfma_f32_16x16x32_bf16 v[12:15], v[150:153], v[206:209], v[12:15]
	v_mfma_f32_16x16x32_bf16 v[12:15], v[146:149], v[202:205], v[12:15]
	s_barrier
	s_cmp_gt_u32 s29, 13
	s_cbranch_scc0 .LBB0_175
	s_and_b64 vcc, exec, s[26:27]
	s_cbranch_vccz .LBB0_178
	s_barrier

.LBB0_380:
	s_add_u32 s86, s24, 0xc000000
	s_addc_u32 s87, s25, 0
	s_add_u32 s34, s24, 0x10000000
	s_addc_u32 s35, s25, 0
	s_add_u32 s42, s24, 0x14000000
	s_addc_u32 s43, s25, 0
	v_writelane_b32 v251, s42, 56
	v_and_b32_e32 v4, 48, v219
	v_lshlrev_b32_e32 v5, 6, v219
	v_writelane_b32 v251, s43, 57
	s_add_u32 s42, s24, 0x18000000
	s_addc_u32 s43, s25, 0
	v_writelane_b32 v251, s42, 58
	s_waitcnt vmcnt(2)
	s_barrier
	s_mov_b32 s53, 0
	v_writelane_b32 v251, s43, 59
	s_add_u32 s42, s24, 0x1c000000
	s_addc_u32 s43, s25, 0
	v_writelane_b32 v251, s42, 60
	s_nop 1
	v_writelane_b32 v251, s43, 61
	s_add_u32 s42, s24, 0x20000000
	s_addc_u32 s43, s25, 0
	v_writelane_b32 v251, s42, 62
	s_nop 1
	v_writelane_b32 v251, s43, 63
	s_add_u32 s42, s24, 0x24000000
	s_addc_u32 s43, s25, 0
	v_writelane_b32 v250, s42, 0
	s_nop 1
	v_writelane_b32 v250, s43, 1
	s_add_u32 s42, s24, 0x28000000
	s_addc_u32 s43, s25, 0
	v_writelane_b32 v250, s42, 2
	s_add_u32 s24, s24, 0x50000
	s_addc_u32 s25, s25, 0
	v_writelane_b32 v250, s43, 3
	v_writelane_b32 v250, s24, 4
	s_lshl_b32 s1, s27, 13
	s_add_i32 m0, s39, 0x18000
	v_writelane_b32 v250, s25, 5
	s_movk_i32 s24, 0x3c0
	v_and_or_b32 v4, v5, s24, v4
	v_lshlrev_b32_e32 v5, 2, v219
	v_and_b32_e32 v5, 32, v5
	v_bitop3_b32 v6, v4, s1, v5 bitop3:0xde
	s_lshl_b32 s1, s26, 5
	s_and_b32 s24, s1, 0x60
	s_lshl_b32 s1, s24, 7
	v_bitop3_b32 v220, s1, v4, v5 bitop3:0xf6
	v_lshl_add_u64 v[4:5], v[0:1], 0, s[10:11]
	global_load_lds_dwordx4 v[4:5], off
	v_lshl_add_u64 v[4:5], v[0:1], 0, s[12:13]
	s_add_i32 m0, s39, 0x1a000
	s_add_i32 s26, s39, 0x8000
	s_lshl_b32 s62, s27, 6
	global_load_lds_dwordx4 v[4:5], off
	v_lshl_add_u64 v[4:5], v[2:3], 0, s[10:11]
	s_mov_b32 m0, s26
	s_add_i32 s27, s39, 0xa000
	global_load_lds_dwordx4 v[4:5], off
	v_lshl_add_u64 v[2:3], v[2:3], 0, s[12:13]
	s_mov_b32 m0, s27
	s_or_b32 s89, s24, 0xfffffe00
	global_load_lds_dwordx4 v[2:3], off
	v_lshl_add_u64 v[2:3], v[0:1], 0, s[14:15]
	s_add_i32 m0, s39, 0x1c000
	v_lshl_add_u64 v[0:1], v[0:1], 0, s[16:17]
	global_load_lds_dwordx4 v[2:3], off
	s_add_i32 m0, s39, 0x1e000
	s_cmpk_lt_u32 s36, 0x100
	global_load_lds_dwordx4 v[0:1], off
	s_waitcnt vmcnt(6)
	s_mov_b32 s88, s24
	s_cselect_b64 s[58:59], -1, 0
	s_ashr_i32 s63, s18, 31
	s_ashr_i32 s52, s19, 31
	v_add_u32_e32 v221, 0, v6
	s_barrier
	s_mov_b32 s98, -1
	s_branch .LBB0_383

.LBB0_383:
	s_not_b32 s98, s98
	s_and_b32 s100, s98, 14
	s_and_b32 s99, s98, 0x200
	s_sub_i32 s99, 0x100, s99
	s_andn2_b32 s101, 0x700, s98
	s_add_i32 s53, s53, 1
	s_mul_i32 s1, s53, s63
	s_mul_hi_u32 s24, s53, s18
	s_add_i32 s1, s24, s1
	s_mul_i32 s24, s53, s18
	s_add_u32 s24, s24, s19
	s_addc_u32 s25, s1, s52
	v_cmp_gt_i64_e32 vcc, s[24:25], v[176:177]
	v_cmp_lt_i64_e64 s[36:37], s[24:25], v[174:175]
	s_cbranch_vccnz .LBB0_385
	s_ashr_i32 s1, s24, 31
	s_lshr_b32 s1, s1, 29
	s_add_i32 s1, s24, s1
	s_ashr_i32 s25, s1, 3
	s_and_b32 s1, s1, -8
	s_sub_i32 s1, s24, s1
	s_cmp_lt_i32 s1, 0
	s_movk_i32 s24, 0x241
	s_cselect_b32 s24, s24, 0x240
	s_mul_i32 s1, s1, s24
	s_add_i32 s1, s1, s25
	s_mul_hi_i32 s24, s1, 0x38e38e39
	s_lshr_b32 s25, s24, 31
	s_ashr_i32 s24, s24, 6
	s_add_i32 s24, s24, s25
	s_lshl_b32 s25, s24, 3
	s_sub_i32 s42, 0x80, s25
	s_min_i32 s42, s42, 8
	s_abs_i32 s43, s42
	v_cvt_f32_u32_e32 v0, s43
	s_sub_i32 s57, 0, s43
	s_mulk_i32 s24, 0x120
	s_sub_i32 s1, s1, s24
	v_rcp_iflag_f32_e32 v0, v0
	s_abs_i32 s24, s1
	s_xor_b32 s56, s1, s42
	s_ashr_i32 s56, s56, 31
	v_mul_f32_e32 v0, 0x4f7ffffe, v0
	v_cvt_u32_f32_e32 v0, v0
	s_nop 0
	v_readfirstlane_b32 s68, v0
	s_mul_i32 s57, s57, s68
	s_mul_hi_u32 s57, s68, s57
	s_add_i32 s68, s68, s57
	s_mul_hi_u32 s57, s24, s68
	s_mul_i32 s68, s57, s43
	s_sub_i32 s24, s24, s68
	s_add_i32 s69, s57, 1
	s_sub_i32 s68, s24, s43
	s_cmp_ge_u32 s24, s43
	s_cselect_b32 s57, s69, s57
	s_cselect_b32 s24, s68, s24
	s_add_i32 s68, s57, 1
	s_cmp_ge_u32 s24, s43
	s_cselect_b32 s24, s68, s57
	s_xor_b32 s24, s24, s56
	s_sub_i32 s78, s24, s56
	s_mul_i32 s24, s78, s42
	s_sub_i32 s1, s1, s24
	s_add_i32 s56, s25, s1
.LBB0_385:
	s_ashr_i32 s57, s56, 31
	s_lshl_b64 s[24:25], s[56:57], 19
	s_add_u32 s24, s48, s24
	s_addc_u32 s25, s49, s25
	s_and_b64 s[42:43], s[36:37], exec
	s_cselect_b32 s1, s25, s9
	s_cselect_b32 s57, s24, s8
	s_ashr_i32 s79, s78, 31
	s_lshl_b64 s[42:43], s[78:79], 19
	s_add_u32 s76, s50, s42
	s_addc_u32 s77, s51, s43
	s_and_b64 s[42:43], s[36:37], exec
	v_mov_b32_e32 v0, 0
	s_cselect_b32 s68, s77, s3
	s_cselect_b32 s69, s76, s2
	s_add_u32 s57, s57, s101
	s_addc_u32 s1, s1, 0
	s_add_u32 s69, s69, s101
	s_addc_u32 s68, s68, 0
	s_mov_b32 s70, -2
	v_mov_b32_e32 v1, v0
	v_mov_b32_e32 v2, v0
	v_mov_b32_e32 v3, v0
	v_mov_b32_e32 v4, v0
	v_mov_b32_e32 v5, v0
	v_mov_b32_e32 v6, v0
	v_mov_b32_e32 v7, v0
	v_mov_b32_e32 v12, v0
	v_mov_b32_e32 v13, v0
	v_mov_b32_e32 v14, v0
	v_mov_b32_e32 v15, v0
	v_mov_b32_e32 v20, v0
	v_mov_b32_e32 v21, v0
	v_mov_b32_e32 v22, v0
	v_mov_b32_e32 v23, v0
	v_mov_b32_e32 v28, v0
	v_mov_b32_e32 v29, v0
	v_mov_b32_e32 v30, v0
	v_mov_b32_e32 v31, v0
	v_mov_b32_e32 v36, v0
	v_mov_b32_e32 v37, v0
	v_mov_b32_e32 v38, v0
	v_mov_b32_e32 v39, v0
	v_mov_b32_e32 v44, v0
	v_mov_b32_e32 v45, v0
	v_mov_b32_e32 v46, v0
	v_mov_b32_e32 v47, v0
	v_mov_b32_e32 v52, v0
	v_mov_b32_e32 v53, v0
	v_mov_b32_e32 v54, v0
	v_mov_b32_e32 v55, v0
	v_mov_b32_e32 v8, v0
	v_mov_b32_e32 v9, v0
	v_mov_b32_e32 v10, v0
	v_mov_b32_e32 v11, v0
	v_mov_b32_e32 v16, v0
	v_mov_b32_e32 v17, v0
	v_mov_b32_e32 v18, v0
	v_mov_b32_e32 v19, v0
	v_mov_b32_e32 v24, v0
	v_mov_b32_e32 v25, v0
	v_mov_b32_e32 v26, v0
	v_mov_b32_e32 v27, v0
	v_mov_b32_e32 v32, v0
	v_mov_b32_e32 v33, v0
	v_mov_b32_e32 v34, v0
	v_mov_b32_e32 v35, v0
	v_mov_b32_e32 v40, v0
	v_mov_b32_e32 v41, v0
	v_mov_b32_e32 v42, v0
	v_mov_b32_e32 v43, v0
	v_mov_b32_e32 v48, v0
	v_mov_b32_e32 v49, v0
	v_mov_b32_e32 v50, v0
	v_mov_b32_e32 v51, v0
	v_mov_b32_e32 v56, v0
	v_mov_b32_e32 v57, v0
	v_mov_b32_e32 v58, v0
	v_mov_b32_e32 v59, v0
	v_mov_b32_e32 v60, v0
	v_mov_b32_e32 v61, v0
	v_mov_b32_e32 v62, v0
	v_mov_b32_e32 v63, v0
	v_mov_b32_e32 v64, v0
	v_mov_b32_e32 v65, v0
	v_mov_b32_e32 v66, v0
	v_mov_b32_e32 v67, v0
	v_mov_b32_e32 v68, v0
	v_mov_b32_e32 v69, v0
	v_mov_b32_e32 v70, v0
	v_mov_b32_e32 v71, v0
	v_mov_b32_e32 v76, v0
	v_mov_b32_e32 v77, v0
	v_mov_b32_e32 v78, v0
	v_mov_b32_e32 v79, v0
	v_mov_b32_e32 v84, v0
	v_mov_b32_e32 v85, v0
	v_mov_b32_e32 v86, v0
	v_mov_b32_e32 v87, v0
	v_mov_b32_e32 v92, v0
	v_mov_b32_e32 v93, v0
	v_mov_b32_e32 v94, v0
	v_mov_b32_e32 v95, v0
	v_mov_b32_e32 v100, v0
	v_mov_b32_e32 v101, v0
	v_mov_b32_e32 v102, v0
	v_mov_b32_e32 v103, v0
	v_mov_b32_e32 v108, v0
	v_mov_b32_e32 v109, v0
	v_mov_b32_e32 v110, v0
	v_mov_b32_e32 v111, v0
	v_mov_b32_e32 v116, v0
	v_mov_b32_e32 v117, v0
	v_mov_b32_e32 v118, v0
	v_mov_b32_e32 v119, v0
	v_mov_b32_e32 v72, v0
	v_mov_b32_e32 v73, v0
	v_mov_b32_e32 v74, v0
	v_mov_b32_e32 v75, v0
	v_mov_b32_e32 v80, v0
	v_mov_b32_e32 v81, v0
	v_mov_b32_e32 v82, v0
	v_mov_b32_e32 v83, v0
	v_mov_b32_e32 v88, v0
	v_mov_b32_e32 v89, v0
	v_mov_b32_e32 v90, v0
	v_mov_b32_e32 v91, v0
	v_mov_b32_e32 v96, v0
	v_mov_b32_e32 v97, v0
	v_mov_b32_e32 v98, v0
	v_mov_b32_e32 v99, v0
	v_mov_b32_e32 v104, v0
	v_mov_b32_e32 v105, v0
	v_mov_b32_e32 v106, v0
	v_mov_b32_e32 v107, v0
	v_mov_b32_e32 v112, v0
	v_mov_b32_e32 v113, v0
	v_mov_b32_e32 v114, v0
	v_mov_b32_e32 v115, v0
	v_mov_b32_e32 v120, v0
	v_mov_b32_e32 v121, v0
	v_mov_b32_e32 v122, v0
	v_mov_b32_e32 v123, v0
	v_mov_b32_e32 v124, v0
	v_mov_b32_e32 v125, v0
	v_mov_b32_e32 v126, v0
	v_mov_b32_e32 v127, v0
.LBB0_386:
	s_add_i32 s70, s70, 2
	s_xor_b32 s42, s70, s100
	s_ashr_i32 s43, s42, 31
	s_lshl_b64 s[72:73], s[42:43], 7
	s_add_i32 s43, s72, s99
	s_mov_b32 s71, 0
	s_add_u32 s79, s8, s43
	s_addc_u32 s80, s9, s71
	s_add_u32 s82, s2, s43
	s_addc_u32 s71, s3, s71
	s_add_i32 s83, 0, 0x10000
	s_cmp_eq_u32 s70, 14
	s_cselect_b32 s43, s1, s80
	s_cselect_b32 s42, s57, s79
	s_cselect_b32 s81, s68, s71
	s_cselect_b32 s80, s69, s82
	s_add_i32 s71, 0, 0x14000
	v_add_u32_e32 v140, s83, v220
	v_add_u32_e32 v156, s71, v220
	s_add_u32 s72, s8, s72
	s_addc_u32 s73, s9, s73
	v_lshl_add_u64 v[222:223], s[72:73], 0, v[182:183]
	v_lshl_add_u64 v[224:225], v[222:223], 0, s[14:15]
	s_add_i32 m0, s39, 0xc000
	s_nop 0
	global_load_lds_dwordx4 v[224:225], off
	v_lshl_add_u64 v[222:223], v[222:223], 0, s[16:17]
	s_add_i32 m0, s39, 0xe000
	s_nop 0
	global_load_lds_dwordx4 v[222:223], off
	ds_read_b128 v[128:131], v140
	ds_read_b128 v[132:135], v140 offset:1024
	ds_read_b128 v[136:139], v140 offset:2048
	ds_read_b128 v[140:143], v140 offset:3072
	ds_read_b128 v[144:147], v156
	ds_read_b128 v[148:151], v156 offset:1024
	ds_read_b128 v[152:155], v156 offset:2048
	ds_read_b128 v[156:159], v156 offset:3072
	ds_read_b128 v[160:163], v221
	ds_read_b128 v[164:167], v221 offset:1024
	ds_read_b128 v[186:189], v221 offset:2048
	ds_read_b128 v[190:193], v221 offset:3072
	ds_read_b128 v[194:197], v221 offset:4096
	ds_read_b128 v[198:201], v221 offset:5120
	ds_read_b128 v[202:205], v221 offset:6144
	ds_read_b128 v[206:209], v221 offset:7168
	s_waitcnt vmcnt(8)
	s_waitcnt lgkmcnt(0)
	s_barrier
	s_waitcnt lgkmcnt(0)
	v_mfma_f32_16x16x32_bf16 v[124:127], v[128:131], v[160:163], v[124:127]
	v_mfma_f32_16x16x32_bf16 v[124:127], v[132:135], v[164:167], v[124:127]
	v_mfma_f32_16x16x32_bf16 v[120:123], v[140:143], v[164:167], v[120:123]
	v_mfma_f32_16x16x32_bf16 v[120:123], v[136:139], v[160:163], v[120:123]
	v_mfma_f32_16x16x32_bf16 v[116:119], v[144:147], v[160:163], v[116:119]
	v_mfma_f32_16x16x32_bf16 v[116:119], v[148:151], v[164:167], v[116:119]
	v_mfma_f32_16x16x32_bf16 v[108:111], v[156:159], v[164:167], v[108:111]
	v_mfma_f32_16x16x32_bf16 v[108:111], v[152:155], v[160:163], v[108:111]
	v_mfma_f32_16x16x32_bf16 v[92:95], v[152:155], v[186:189], v[92:95]
	v_mfma_f32_16x16x32_bf16 v[92:95], v[156:159], v[190:193], v[92:95]
	v_mfma_f32_16x16x32_bf16 v[100:103], v[148:151], v[190:193], v[100:103]
	v_mfma_f32_16x16x32_bf16 v[100:103], v[144:147], v[186:189], v[100:103]
	v_mfma_f32_16x16x32_bf16 v[104:107], v[136:139], v[186:189], v[104:107]
	v_mfma_f32_16x16x32_bf16 v[104:107], v[140:143], v[190:193], v[104:107]
	v_mfma_f32_16x16x32_bf16 v[112:115], v[132:135], v[190:193], v[112:115]
	v_mfma_f32_16x16x32_bf16 v[112:115], v[128:131], v[186:189], v[112:115]
	v_mfma_f32_16x16x32_bf16 v[96:99], v[128:131], v[194:197], v[96:99]
	v_mfma_f32_16x16x32_bf16 v[96:99], v[132:135], v[198:201], v[96:99]
	v_mfma_f32_16x16x32_bf16 v[88:91], v[140:143], v[198:201], v[88:91]
	v_mfma_f32_16x16x32_bf16 v[88:91], v[136:139], v[194:197], v[88:91]
	v_mfma_f32_16x16x32_bf16 v[84:87], v[144:147], v[194:197], v[84:87]
	v_mfma_f32_16x16x32_bf16 v[84:87], v[148:151], v[198:201], v[84:87]
	v_mfma_f32_16x16x32_bf16 v[76:79], v[156:159], v[198:201], v[76:79]
	v_mfma_f32_16x16x32_bf16 v[76:79], v[152:155], v[194:197], v[76:79]
	v_mfma_f32_16x16x32_bf16 v[64:67], v[152:155], v[202:205], v[64:67]
	v_mfma_f32_16x16x32_bf16 v[64:67], v[156:159], v[206:209], v[64:67]
	v_mfma_f32_16x16x32_bf16 v[68:71], v[148:151], v[206:209], v[68:71]
	v_mfma_f32_16x16x32_bf16 v[68:71], v[144:147], v[202:205], v[68:71]
	v_mfma_f32_16x16x32_bf16 v[72:75], v[136:139], v[202:205], v[72:75]
	v_mfma_f32_16x16x32_bf16 v[72:75], v[140:143], v[206:209], v[72:75]
	v_mfma_f32_16x16x32_bf16 v[80:83], v[132:135], v[206:209], v[80:83]
	v_mfma_f32_16x16x32_bf16 v[80:83], v[128:131], v[202:205], v[80:83]
	s_barrier
	s_add_i32 s72, s83, s74
	v_lshl_add_u64 v[222:223], s[80:81], 0, v[184:185]
	s_mov_b32 m0, s72
	s_nop 0
	global_load_lds_dwordx4 v[222:223], off
	v_lshl_add_u64 v[224:225], v[222:223], 0, s[40:41]
	s_add_i32 m0, s72, 0x2000
	s_add_i32 s71, s71, s74
	global_load_lds_dwordx4 v[224:225], off
	v_lshl_add_u64 v[224:225], v[222:223], 0, s[4:5]
	s_mov_b32 m0, s71
	s_nop 0
	global_load_lds_dwordx4 v[224:225], off
	v_lshl_add_u64 v[224:225], v[222:223], 0, s[6:7]
	s_add_i32 m0, s71, 0x2000
	s_nop 0
	global_load_lds_dwordx4 v[224:225], off
	v_lshl_add_u64 v[224:225], s[42:43], 0, v[182:183]
	s_mov_b32 m0, s39
	v_lshl_add_u64 v[226:227], v[224:225], 0, s[40:41]
	global_load_lds_dwordx4 v[224:225], off
	s_mov_b32 m0, s75
	s_nop 0
	global_load_lds_dwordx4 v[226:227], off
	ds_read_b128 v[160:163], v221 offset:16384
	ds_read_b128 v[164:167], v221 offset:17408
	ds_read_b128 v[186:189], v221 offset:18432
	ds_read_b128 v[190:193], v221 offset:19456
	ds_read_b128 v[194:197], v221 offset:20480
	ds_read_b128 v[198:201], v221 offset:21504
	ds_read_b128 v[202:205], v221 offset:22528
	ds_read_b128 v[206:209], v221 offset:23552
	s_waitcnt vmcnt(8)
	s_waitcnt lgkmcnt(0)
	s_barrier
	s_waitcnt lgkmcnt(0)
	v_mfma_f32_16x16x32_bf16 v[60:63], v[128:131], v[160:163], v[60:63]
	v_mfma_f32_16x16x32_bf16 v[60:63], v[132:135], v[164:167], v[60:63]
	v_mfma_f32_16x16x32_bf16 v[56:59], v[140:143], v[164:167], v[56:59]
	v_mfma_f32_16x16x32_bf16 v[56:59], v[136:139], v[160:163], v[56:59]
	v_mfma_f32_16x16x32_bf16 v[52:55], v[144:147], v[160:163], v[52:55]
	v_mfma_f32_16x16x32_bf16 v[52:55], v[148:151], v[164:167], v[52:55]
	v_mfma_f32_16x16x32_bf16 v[44:47], v[156:159], v[164:167], v[44:47]
	v_mfma_f32_16x16x32_bf16 v[44:47], v[152:155], v[160:163], v[44:47]
	v_mfma_f32_16x16x32_bf16 v[28:31], v[152:155], v[186:189], v[28:31]
	v_mfma_f32_16x16x32_bf16 v[28:31], v[156:159], v[190:193], v[28:31]
	v_mfma_f32_16x16x32_bf16 v[36:39], v[148:151], v[190:193], v[36:39]
	v_mfma_f32_16x16x32_bf16 v[36:39], v[144:147], v[186:189], v[36:39]
	v_mfma_f32_16x16x32_bf16 v[40:43], v[136:139], v[186:189], v[40:43]
	v_mfma_f32_16x16x32_bf16 v[40:43], v[140:143], v[190:193], v[40:43]
	v_mfma_f32_16x16x32_bf16 v[48:51], v[132:135], v[190:193], v[48:51]
	v_mfma_f32_16x16x32_bf16 v[48:51], v[128:131], v[186:189], v[48:51]
	v_mfma_f32_16x16x32_bf16 v[32:35], v[128:131], v[194:197], v[32:35]
	v_mfma_f32_16x16x32_bf16 v[32:35], v[132:135], v[198:201], v[32:35]
	v_mfma_f32_16x16x32_bf16 v[24:27], v[140:143], v[198:201], v[24:27]
	v_mfma_f32_16x16x32_bf16 v[24:27], v[136:139], v[194:197], v[24:27]
	v_mfma_f32_16x16x32_bf16 v[20:23], v[144:147], v[194:197], v[20:23]
	v_mfma_f32_16x16x32_bf16 v[20:23], v[148:151], v[198:201], v[20:23]
	v_mfma_f32_16x16x32_bf16 v[12:15], v[156:159], v[198:201], v[12:15]
	v_mfma_f32_16x16x32_bf16 v[12:15], v[152:155], v[194:197], v[12:15]
	v_mfma_f32_16x16x32_bf16 v[0:3], v[152:155], v[202:205], v[0:3]
	v_mfma_f32_16x16x32_bf16 v[0:3], v[156:159], v[206:209], v[0:3]
	v_mfma_f32_16x16x32_bf16 v[4:7], v[148:151], v[206:209], v[4:7]
	v_mfma_f32_16x16x32_bf16 v[4:7], v[144:147], v[202:205], v[4:7]
	v_mfma_f32_16x16x32_bf16 v[8:11], v[136:139], v[202:205], v[8:11]
	v_mfma_f32_16x16x32_bf16 v[8:11], v[140:143], v[206:209], v[8:11]
	v_mfma_f32_16x16x32_bf16 v[16:19], v[132:135], v[206:209], v[16:19]
	v_mfma_f32_16x16x32_bf16 v[16:19], v[128:131], v[202:205], v[16:19]
	s_barrier
	s_add_i32 s42, 0, 0x18000
	s_add_i32 s43, 0, 0x1c000
	v_add_u32_e32 v140, s42, v220
	v_add_u32_e32 v156, s43, v220
	s_mov_b32 m0, s30
	v_lshl_add_u64 v[226:227], v[224:225], 0, s[4:5]
	global_load_lds_dwordx4 v[226:227], off
	v_lshl_add_u64 v[226:227], v[224:225], 0, s[6:7]
	s_mov_b32 m0, s31
	s_nop 0
	global_load_lds_dwordx4 v[226:227], off
	ds_read_b128 v[128:131], v140
	ds_read_b128 v[132:135], v140 offset:1024
	ds_read_b128 v[136:139], v140 offset:2048
	ds_read_b128 v[140:143], v140 offset:3072
	ds_read_b128 v[144:147], v156
	ds_read_b128 v[148:151], v156 offset:1024
	ds_read_b128 v[152:155], v156 offset:2048
	ds_read_b128 v[156:159], v156 offset:3072
	ds_read_b128 v[160:163], v221 offset:32768
	ds_read_b128 v[164:167], v221 offset:33792
	ds_read_b128 v[186:189], v221 offset:34816
	ds_read_b128 v[190:193], v221 offset:35840
	ds_read_b128 v[194:197], v221 offset:36864
	ds_read_b128 v[198:201], v221 offset:37888
	ds_read_b128 v[202:205], v221 offset:38912
	ds_read_b128 v[206:209], v221 offset:39936
	s_waitcnt vmcnt(8)
	s_waitcnt lgkmcnt(0)
	s_barrier
	s_waitcnt lgkmcnt(0)
	v_mfma_f32_16x16x32_bf16 v[124:127], v[128:131], v[160:163], v[124:127]
	v_mfma_f32_16x16x32_bf16 v[124:127], v[132:135], v[164:167], v[124:127]
	v_mfma_f32_16x16x32_bf16 v[120:123], v[140:143], v[164:167], v[120:123]
	v_mfma_f32_16x16x32_bf16 v[120:123], v[136:139], v[160:163], v[120:123]
	v_mfma_f32_16x16x32_bf16 v[116:119], v[144:147], v[160:163], v[116:119]
	v_mfma_f32_16x16x32_bf16 v[116:119], v[148:151], v[164:167], v[116:119]
	v_mfma_f32_16x16x32_bf16 v[108:111], v[156:159], v[164:167], v[108:111]
	v_mfma_f32_16x16x32_bf16 v[108:111], v[152:155], v[160:163], v[108:111]
	v_mfma_f32_16x16x32_bf16 v[92:95], v[152:155], v[186:189], v[92:95]
	v_mfma_f32_16x16x32_bf16 v[92:95], v[156:159], v[190:193], v[92:95]
	v_mfma_f32_16x16x32_bf16 v[100:103], v[148:151], v[190:193], v[100:103]
	v_mfma_f32_16x16x32_bf16 v[100:103], v[144:147], v[186:189], v[100:103]
	v_mfma_f32_16x16x32_bf16 v[104:107], v[136:139], v[186:189], v[104:107]
	v_mfma_f32_16x16x32_bf16 v[104:107], v[140:143], v[190:193], v[104:107]
	v_mfma_f32_16x16x32_bf16 v[112:115], v[132:135], v[190:193], v[112:115]
	v_mfma_f32_16x16x32_bf16 v[112:115], v[128:131], v[186:189], v[112:115]
	v_mfma_f32_16x16x32_bf16 v[96:99], v[128:131], v[194:197], v[96:99]
	v_mfma_f32_16x16x32_bf16 v[96:99], v[132:135], v[198:201], v[96:99]
	v_mfma_f32_16x16x32_bf16 v[88:91], v[140:143], v[198:201], v[88:91]
	v_mfma_f32_16x16x32_bf16 v[88:91], v[136:139], v[194:197], v[88:91]
	v_mfma_f32_16x16x32_bf16 v[84:87], v[144:147], v[194:197], v[84:87]
	v_mfma_f32_16x16x32_bf16 v[84:87], v[148:151], v[198:201], v[84:87]
	v_mfma_f32_16x16x32_bf16 v[76:79], v[156:159], v[198:201], v[76:79]
	v_mfma_f32_16x16x32_bf16 v[76:79], v[152:155], v[194:197], v[76:79]
	v_mfma_f32_16x16x32_bf16 v[64:67], v[152:155], v[202:205], v[64:67]
	v_mfma_f32_16x16x32_bf16 v[64:67], v[156:159], v[206:209], v[64:67]
	v_mfma_f32_16x16x32_bf16 v[68:71], v[148:151], v[206:209], v[68:71]
	v_mfma_f32_16x16x32_bf16 v[68:71], v[144:147], v[202:205], v[68:71]
	v_mfma_f32_16x16x32_bf16 v[72:75], v[136:139], v[202:205], v[72:75]
	v_mfma_f32_16x16x32_bf16 v[72:75], v[140:143], v[206:209], v[72:75]
	v_mfma_f32_16x16x32_bf16 v[80:83], v[132:135], v[206:209], v[80:83]
	v_mfma_f32_16x16x32_bf16 v[80:83], v[128:131], v[202:205], v[80:83]
	s_barrier
	s_add_i32 s42, s42, s74
	v_lshl_add_u64 v[226:227], v[222:223], 0, s[10:11]
	s_mov_b32 m0, s42
	s_nop 0
	global_load_lds_dwordx4 v[226:227], off
	v_lshl_add_u64 v[226:227], v[222:223], 0, s[12:13]
	s_add_i32 m0, s42, 0x2000
	s_add_i32 s42, s43, s74
	global_load_lds_dwordx4 v[226:227], off
	v_lshl_add_u64 v[226:227], v[222:223], 0, s[14:15]
	s_mov_b32 m0, s42
	v_lshl_add_u64 v[222:223], v[222:223], 0, s[16:17]
	global_load_lds_dwordx4 v[226:227], off
	s_add_i32 m0, s42, 0x2000
	s_nop 0
	global_load_lds_dwordx4 v[222:223], off
	v_lshl_add_u64 v[222:223], v[224:225], 0, s[10:11]
	s_mov_b32 m0, s26
	s_nop 0
	global_load_lds_dwordx4 v[222:223], off
	v_lshl_add_u64 v[222:223], v[224:225], 0, s[12:13]
	s_mov_b32 m0, s27
	s_nop 0
	global_load_lds_dwordx4 v[222:223], off
	ds_read_b128 v[160:163], v221 offset:49152
	ds_read_b128 v[164:167], v221 offset:50176
	ds_read_b128 v[186:189], v221 offset:51200
	ds_read_b128 v[190:193], v221 offset:52224
	ds_read_b128 v[194:197], v221 offset:53248
	ds_read_b128 v[198:201], v221 offset:54272
	ds_read_b128 v[202:205], v221 offset:55296
	ds_read_b128 v[206:209], v221 offset:56320
	s_waitcnt vmcnt(8)
	s_waitcnt lgkmcnt(0)
	s_barrier
	s_waitcnt lgkmcnt(0)
	v_mfma_f32_16x16x32_bf16 v[60:63], v[128:131], v[160:163], v[60:63]
	v_mfma_f32_16x16x32_bf16 v[60:63], v[132:135], v[164:167], v[60:63]
	v_mfma_f32_16x16x32_bf16 v[56:59], v[140:143], v[164:167], v[56:59]
	v_mfma_f32_16x16x32_bf16 v[56:59], v[136:139], v[160:163], v[56:59]
	v_mfma_f32_16x16x32_bf16 v[52:55], v[144:147], v[160:163], v[52:55]
	v_mfma_f32_16x16x32_bf16 v[52:55], v[148:151], v[164:167], v[52:55]
	v_mfma_f32_16x16x32_bf16 v[44:47], v[156:159], v[164:167], v[44:47]
	v_mfma_f32_16x16x32_bf16 v[44:47], v[152:155], v[160:163], v[44:47]
	v_mfma_f32_16x16x32_bf16 v[28:31], v[152:155], v[186:189], v[28:31]
	v_mfma_f32_16x16x32_bf16 v[28:31], v[156:159], v[190:193], v[28:31]
	v_mfma_f32_16x16x32_bf16 v[36:39], v[148:151], v[190:193], v[36:39]
	v_mfma_f32_16x16x32_bf16 v[36:39], v[144:147], v[186:189], v[36:39]
	v_mfma_f32_16x16x32_bf16 v[40:43], v[136:139], v[186:189], v[40:43]
	v_mfma_f32_16x16x32_bf16 v[40:43], v[140:143], v[190:193], v[40:43]
	v_mfma_f32_16x16x32_bf16 v[48:51], v[132:135], v[190:193], v[48:51]
	v_mfma_f32_16x16x32_bf16 v[48:51], v[128:131], v[186:189], v[48:51]
	v_mfma_f32_16x16x32_bf16 v[32:35], v[128:131], v[194:197], v[32:35]
	v_mfma_f32_16x16x32_bf16 v[32:35], v[132:135], v[198:201], v[32:35]
	v_mfma_f32_16x16x32_bf16 v[24:27], v[140:143], v[198:201], v[24:27]
	v_mfma_f32_16x16x32_bf16 v[24:27], v[136:139], v[194:197], v[24:27]
	v_mfma_f32_16x16x32_bf16 v[20:23], v[144:147], v[194:197], v[20:23]
	v_mfma_f32_16x16x32_bf16 v[20:23], v[148:151], v[198:201], v[20:23]
	v_mfma_f32_16x16x32_bf16 v[12:15], v[156:159], v[198:201], v[12:15]
	v_mfma_f32_16x16x32_bf16 v[12:15], v[152:155], v[194:197], v[12:15]
	v_mfma_f32_16x16x32_bf16 v[0:3], v[152:155], v[202:205], v[0:3]
	v_mfma_f32_16x16x32_bf16 v[0:3], v[156:159], v[206:209], v[0:3]
	v_mfma_f32_16x16x32_bf16 v[4:7], v[148:151], v[206:209], v[4:7]
	v_mfma_f32_16x16x32_bf16 v[4:7], v[144:147], v[202:205], v[4:7]
	v_mfma_f32_16x16x32_bf16 v[8:11], v[136:139], v[202:205], v[8:11]
	v_mfma_f32_16x16x32_bf16 v[8:11], v[140:143], v[206:209], v[8:11]
	v_mfma_f32_16x16x32_bf16 v[16:19], v[132:135], v[206:209], v[16:19]
	v_mfma_f32_16x16x32_bf16 v[16:19], v[128:131], v[202:205], v[16:19]
	s_barrier
	s_cmp_gt_u32 s70, 13
	s_cbranch_scc0 .LBB0_386
	s_and_b64 vcc, exec, s[58:59]
	s_cbranch_vccz .LBB0_389
	s_barrier

.LBB0_964:
	s_add_u32 s8, s8, 0x14000000
	s_mov_b64 s[10:11], 0x80
	s_addc_u32 s9, s9, 0
	v_lshl_add_u64 v[4:5], v[0:1], 0, s[10:11]
	s_add_i32 m0, s48, 0x18000
	s_mov_b64 s[12:13], 0x20080
	s_waitcnt vmcnt(2)
	s_barrier
	global_load_lds_dwordx4 v[4:5], off
	v_lshl_add_u64 v[4:5], v[0:1], 0, s[12:13]
	s_add_i32 m0, s48, 0x1a000
	s_add_i32 s53, s48, 0x8000
	global_load_lds_dwordx4 v[4:5], off
	v_lshl_add_u64 v[4:5], v[2:3], 0, s[10:11]
	s_mov_b32 m0, s53
	s_add_i32 s54, s48, 0xa000
	global_load_lds_dwordx4 v[4:5], off
	v_lshl_add_u64 v[2:3], v[2:3], 0, s[12:13]
	s_mov_b32 m0, s54
	s_mov_b64 s[14:15], 0x40080
	global_load_lds_dwordx4 v[2:3], off
	v_lshl_add_u64 v[2:3], v[0:1], 0, s[14:15]
	s_add_i32 m0, s48, 0x1c000
	s_mov_b64 s[16:17], 0x60080
	global_load_lds_dwordx4 v[2:3], off
	v_lshl_add_u64 v[0:1], v[0:1], 0, s[16:17]
	s_add_i32 m0, s48, 0x1e000
	s_sext_i32_i16 s29, s18
	global_load_lds_dwordx4 v[0:1], off
	s_lshl_b32 s55, s21, 6
	v_and_b32_e32 v0, 48, v138
	s_lshl_b32 s18, s21, 13
	v_lshlrev_b32_e32 v1, 6, v138
	s_movk_i32 s21, 0x3c0
	v_and_or_b32 v0, v1, s21, v0
	v_lshlrev_b32_e32 v1, 2, v138
	v_and_b32_e32 v1, 32, v1
	v_bitop3_b32 v2, v0, s18, v1 bitop3:0xde
	s_lshl_b32 s18, s20, 5
	s_and_b32 s56, s18, 0x60
	s_lshl_b32 s18, s56, 7
	s_cmpk_lt_u32 s19, 0x100
	v_bitop3_b32 v139, s18, v0, v1 bitop3:0xf6
	s_waitcnt vmcnt(0)
	s_cselect_b64 s[18:19], -1, 0
	s_add_i32 s61, 0, 0x10000
	s_add_i32 s63, 0, 0x14000
	v_add_u32_e32 v140, s61, v139
	v_add_u32_e32 v141, s63, v139
	s_add_i32 s61, s61, s45
	s_add_i32 s63, s63, s45
	s_add_i32 s65, 0, 0x18000
	s_ashr_i32 s57, s33, 31
	v_mov_b64_e32 v[132:133], 0x1600
	v_mov_b64_e32 v[134:135], 0x15ff
	v_add_u32_e32 v142, 0, v2
	s_movk_i32 s58, 0x1600
	s_add_i32 s59, s48, 0xc000
	s_add_i32 s60, s48, 0xe000
	s_add_i32 s62, s61, 0x2000
	s_add_i32 s64, s63, 0x2000
	v_add_u32_e32 v143, s65, v139
	s_barrier
	s_mov_b32 s98, -1
	s_branch .LBB0_967

.LBB0_967:
	s_not_b32 s98, s98
	s_and_b32 s100, s98, 14
	s_and_b32 s99, s98, 0x200
	s_sub_i32 s99, 0x100, s99
	s_andn2_b32 s101, 0x700, s98
	s_add_i32 s52, s52, 1
	s_mul_i32 s21, s52, s57
	s_mul_hi_u32 s23, s52, s33
	s_add_i32 s23, s23, s21
	s_mul_i32 s21, s52, s33
	s_add_u32 s24, s21, s40
	s_addc_u32 s25, s23, s46
	v_cmp_gt_i64_e32 vcc, s[24:25], v[134:135]
	v_cmp_lt_i64_e64 s[36:37], s[24:25], v[132:133]
	s_cbranch_vccnz .LBB0_969
	s_ashr_i32 s20, s24, 31
	s_lshr_b32 s20, s20, 29
	s_add_i32 s20, s24, s20
	s_ashr_i32 s21, s20, 3
	s_and_b32 s20, s20, -8
	s_sub_i32 s20, s24, s20
	s_cmp_lt_i32 s20, 0
	s_cselect_b32 s22, s47, 0x2c0
	s_mul_i32 s20, s20, s22
	s_add_i32 s20, s20, s21
	s_mul_hi_i32 s21, s20, 0x2e8ba2e9
	s_lshr_b32 s22, s21, 31
	s_ashr_i32 s21, s21, 5
	s_add_i32 s21, s21, s22
	s_lshl_b32 s22, s21, 3
	s_sub_i32 s23, 0x100, s22
	s_min_i32 s23, s23, 8
	s_abs_i32 s24, s23
	v_cvt_f32_u32_e32 v0, s24
	s_sub_i32 s26, 0, s24
	s_mulk_i32 s21, 0xb0
	s_sub_i32 s21, s20, s21
	v_rcp_iflag_f32_e32 v0, v0
	s_abs_i32 s20, s21
	s_xor_b32 s25, s21, s23
	s_ashr_i32 s25, s25, 31
	v_mul_f32_e32 v0, 0x4f7ffffe, v0
	v_cvt_u32_f32_e32 v0, v0
	s_nop 0
	v_readfirstlane_b32 s27, v0
	s_mul_i32 s26, s26, s27
	s_mul_hi_u32 s26, s27, s26
	s_add_i32 s27, s27, s26
	s_mul_hi_u32 s26, s20, s27
	s_mul_i32 s27, s26, s24
	s_sub_i32 s20, s20, s27
	s_add_i32 s38, s26, 1
	s_sub_i32 s27, s20, s24
	s_cmp_ge_u32 s20, s24
	s_cselect_b32 s26, s38, s26
	s_cselect_b32 s20, s27, s20
	s_add_i32 s27, s26, 1
	s_cmp_ge_u32 s20, s24
	s_cselect_b32 s20, s27, s26
	s_xor_b32 s20, s20, s25
	s_sub_i32 s20, s20, s25
	s_mul_i32 s23, s20, s23
	s_sub_i32 s21, s21, s23
	s_add_i32 s22, s22, s21
.LBB0_969:
	s_ashr_i32 s23, s22, 31
	s_lshl_b64 s[24:25], s[22:23], 19
	s_add_u32 s24, s41, s24
	s_addc_u32 s25, s42, s25
	s_ashr_i32 s21, s20, 31
	s_lshl_b64 s[26:27], s[20:21], 19
	s_add_u32 s26, s43, s26
	s_mov_b32 s38, s100
	s_addc_u32 s27, s44, s27
	s_ashr_i32 s39, s38, 31
	s_lshl_b64 s[68:69], s[38:39], 7
	s_add_i32 s70, s68, s99
	s_mov_b32 s71, 0
	s_add_u32 s38, s34, s70
	ds_read_b128 v[0:3], v140
	ds_read_b128 v[4:7], v140 offset:1024
	ds_read_b128 v[8:11], v140 offset:2048
	ds_read_b128 v[12:15], v140 offset:3072
	ds_read_b128 v[16:19], v141
	ds_read_b128 v[20:23], v141 offset:1024
	ds_read_b128 v[24:27], v141 offset:2048
	ds_read_b128 v[28:31], v141 offset:3072
	s_addc_u32 s39, s35, s71
	s_and_b64 s[66:67], s[36:37], exec
	s_cselect_b32 s23, s27, s31
	s_cselect_b32 s66, s26, s30
	s_add_u32 s70, s30, s70
	s_addc_u32 s71, s31, s71
	s_add_u32 s68, s34, s68
	s_mov_b32 s21, 0
	s_addc_u32 s69, s35, s69
	v_lshl_add_u64 v[64:65], s[68:69], 0, v[130:131]
	s_mov_b32 m0, s59
	v_lshl_add_u64 v[66:67], v[64:65], 0, s[14:15]
	ds_read_b128 v[32:35], v142
	ds_read_b128 v[36:39], v142 offset:1024
	ds_read_b128 v[40:43], v142 offset:2048
	ds_read_b128 v[44:47], v142 offset:3072
	ds_read_b128 v[48:51], v142 offset:4096
	ds_read_b128 v[52:55], v142 offset:5120
	ds_read_b128 v[56:59], v142 offset:6144
	ds_read_b128 v[60:63], v142 offset:7168
	global_load_lds_dwordx4 v[66:67], off
	v_lshl_add_u64 v[64:65], v[64:65], 0, s[16:17]
	s_mov_b32 m0, s60
	s_and_b64 s[68:69], s[36:37], exec
	global_load_lds_dwordx4 v[64:65], off
	s_waitcnt vmcnt(16)
	s_waitcnt lgkmcnt(0)
	s_cselect_b32 s67, s25, s35
	s_cselect_b32 s68, s24, s34
	s_add_u32 s66, s66, s101
	s_addc_u32 s23, s23, 0
	s_add_u32 s68, s68, s101
	s_addc_u32 s67, s67, 0
	s_barrier
	s_waitcnt lgkmcnt(0)
	v_mfma_f32_16x16x32_bf16 v[64:67], v[0:3], v[32:35], 0
	v_mfma_f32_16x16x32_bf16 v[68:71], v[8:11], v[32:35], 0
	v_mfma_f32_16x16x32_bf16 v[72:75], v[0:3], v[40:43], 0
	v_mfma_f32_16x16x32_bf16 v[76:79], v[8:11], v[40:43], 0
	v_mfma_f32_16x16x32_bf16 v[80:83], v[0:3], v[48:51], 0
	v_mfma_f32_16x16x32_bf16 v[84:87], v[8:11], v[48:51], 0
	v_mfma_f32_16x16x32_bf16 v[88:91], v[0:3], v[56:59], 0
	v_mfma_f32_16x16x32_bf16 v[92:95], v[8:11], v[56:59], 0
	v_mfma_f32_16x16x32_bf16 v[64:67], v[4:7], v[36:39], v[64:67]
	v_mfma_f32_16x16x32_bf16 v[68:71], v[12:15], v[36:39], v[68:71]
	v_mfma_f32_16x16x32_bf16 v[72:75], v[4:7], v[44:47], v[72:75]
	v_mfma_f32_16x16x32_bf16 v[76:79], v[12:15], v[44:47], v[76:79]
	v_mfma_f32_16x16x32_bf16 v[80:83], v[4:7], v[52:55], v[80:83]
	v_mfma_f32_16x16x32_bf16 v[84:87], v[12:15], v[52:55], v[84:87]
	v_mfma_f32_16x16x32_bf16 v[88:91], v[4:7], v[60:63], v[88:91]
	v_mfma_f32_16x16x32_bf16 v[100:103], v[12:15], v[60:63], v[92:95]
	v_mfma_f32_16x16x32_bf16 v[92:95], v[16:19], v[32:35], 0
	v_mfma_f32_16x16x32_bf16 v[32:35], v[24:27], v[32:35], 0
	v_mfma_f32_16x16x32_bf16 v[104:107], v[20:23], v[36:39], v[92:95]
	v_mfma_f32_16x16x32_bf16 v[32:35], v[28:31], v[36:39], v[32:35]
	v_mfma_f32_16x16x32_bf16 v[36:39], v[16:19], v[40:43], 0
	v_mfma_f32_16x16x32_bf16 v[40:43], v[24:27], v[40:43], 0
	v_mfma_f32_16x16x32_bf16 v[36:39], v[20:23], v[44:47], v[36:39]
	v_mfma_f32_16x16x32_bf16 v[40:43], v[28:31], v[44:47], v[40:43]
	v_mfma_f32_16x16x32_bf16 v[44:47], v[16:19], v[48:51], 0
	v_mfma_f32_16x16x32_bf16 v[48:51], v[24:27], v[48:51], 0
	v_mfma_f32_16x16x32_bf16 v[44:47], v[20:23], v[52:55], v[44:47]
	v_mfma_f32_16x16x32_bf16 v[48:51], v[28:31], v[52:55], v[48:51]
	v_mfma_f32_16x16x32_bf16 v[52:55], v[16:19], v[56:59], 0
	v_mfma_f32_16x16x32_bf16 v[56:59], v[24:27], v[56:59], 0
	v_mfma_f32_16x16x32_bf16 v[52:55], v[20:23], v[60:63], v[52:55]
	v_mfma_f32_16x16x32_bf16 v[56:59], v[28:31], v[60:63], v[56:59]
	s_barrier
	s_mov_b32 m0, s61
	v_lshl_add_u64 v[208:209], s[70:71], 0, v[128:129]
	global_load_lds_dwordx4 v[208:209], off
	v_lshl_add_u64 v[136:137], v[208:209], 0, s[0:1]
	s_mov_b32 m0, s62
	v_lshl_add_u64 v[248:249], s[38:39], 0, v[130:131]
	global_load_lds_dwordx4 v[136:137], off
	v_lshl_add_u64 v[136:137], v[208:209], 0, s[2:3]
	s_mov_b32 m0, s63
	s_nop 0
	global_load_lds_dwordx4 v[136:137], off
	v_lshl_add_u64 v[136:137], v[208:209], 0, s[4:5]
	s_mov_b32 m0, s64
	s_nop 0
	global_load_lds_dwordx4 v[136:137], off
	s_mov_b32 m0, s48
	v_lshl_add_u64 v[136:137], v[248:249], 0, s[0:1]
	global_load_lds_dwordx4 v[248:249], off
	s_mov_b32 m0, s49
	s_nop 0
	global_load_lds_dwordx4 v[136:137], off
	ds_read_b128 v[60:63], v142 offset:16384
	ds_read_b128 v[92:95], v142 offset:17408
	ds_read_b128 v[96:99], v142 offset:18432
	ds_read_b128 v[108:111], v142 offset:19456
	ds_read_b128 v[112:115], v142 offset:20480
	ds_read_b128 v[116:119], v142 offset:21504
	ds_read_b128 v[120:123], v142 offset:22528
	ds_read_b128 v[124:127], v142 offset:23552
	s_waitcnt vmcnt(16)
	s_waitcnt lgkmcnt(0)
	s_barrier
	s_waitcnt lgkmcnt(0)
	v_mfma_f32_16x16x32_bf16 v[144:147], v[0:3], v[60:63], 0
	v_mfma_f32_16x16x32_bf16 v[152:155], v[0:3], v[96:99], 0
	v_mfma_f32_16x16x32_bf16 v[160:163], v[0:3], v[112:115], 0
	v_mfma_f32_16x16x32_bf16 v[0:3], v[0:3], v[120:123], 0
	v_mfma_f32_16x16x32_bf16 v[144:147], v[4:7], v[92:95], v[144:147]
	v_mfma_f32_16x16x32_bf16 v[152:155], v[4:7], v[108:111], v[152:155]
	v_mfma_f32_16x16x32_bf16 v[160:163], v[4:7], v[116:119], v[160:163]
	v_mfma_f32_16x16x32_bf16 v[0:3], v[4:7], v[124:127], v[0:3]
	v_mfma_f32_16x16x32_bf16 v[4:7], v[8:11], v[120:123], 0
	v_mfma_f32_16x16x32_bf16 v[148:151], v[8:11], v[60:63], 0
	v_mfma_f32_16x16x32_bf16 v[156:159], v[8:11], v[96:99], 0
	v_mfma_f32_16x16x32_bf16 v[164:167], v[8:11], v[112:115], 0
	v_mfma_f32_16x16x32_bf16 v[4:7], v[12:15], v[124:127], v[4:7]
	v_mfma_f32_16x16x32_bf16 v[148:151], v[12:15], v[92:95], v[148:151]
	v_mfma_f32_16x16x32_bf16 v[156:159], v[12:15], v[108:111], v[156:159]
	v_mfma_f32_16x16x32_bf16 v[164:167], v[12:15], v[116:119], v[164:167]
	v_mfma_f32_16x16x32_bf16 v[12:15], v[24:27], v[60:63], 0
	v_mfma_f32_16x16x32_bf16 v[172:175], v[28:31], v[92:95], v[12:15]
	v_mfma_f32_16x16x32_bf16 v[12:15], v[16:19], v[96:99], 0
	v_mfma_f32_16x16x32_bf16 v[176:179], v[20:23], v[108:111], v[12:15]
	v_mfma_f32_16x16x32_bf16 v[12:15], v[24:27], v[96:99], 0
	v_mfma_f32_16x16x32_bf16 v[180:183], v[28:31], v[108:111], v[12:15]
	v_mfma_f32_16x16x32_bf16 v[12:15], v[16:19], v[112:115], 0
	v_mfma_f32_16x16x32_bf16 v[184:187], v[20:23], v[116:119], v[12:15]
	v_mfma_f32_16x16x32_bf16 v[12:15], v[24:27], v[112:115], 0
	v_mfma_f32_16x16x32_bf16 v[8:11], v[16:19], v[60:63], 0
	v_mfma_f32_16x16x32_bf16 v[188:191], v[28:31], v[116:119], v[12:15]
	v_mfma_f32_16x16x32_bf16 v[12:15], v[16:19], v[120:123], 0
	v_mfma_f32_16x16x32_bf16 v[8:11], v[20:23], v[92:95], v[8:11]
	v_mfma_f32_16x16x32_bf16 v[192:195], v[20:23], v[124:127], v[12:15]
	v_mfma_f32_16x16x32_bf16 v[12:15], v[24:27], v[120:123], 0
	v_mfma_f32_16x16x32_bf16 v[196:199], v[28:31], v[124:127], v[12:15]
	s_barrier
	s_add_i32 s71, 0, 0x1c000
	v_add_u32_e32 v136, s71, v139
	s_nop 2
	s_mov_b32 m0, s50
	v_lshl_add_u64 v[92:93], v[248:249], 0, s[2:3]
	global_load_lds_dwordx4 v[92:93], off
	v_lshl_add_u64 v[92:93], v[248:249], 0, s[4:5]
	s_mov_b32 m0, s51
	s_nop 0
	global_load_lds_dwordx4 v[92:93], off
	ds_read_b128 v[12:15], v143
	ds_read_b128 v[20:23], v143 offset:1024
	ds_read_b128 v[24:27], v143 offset:2048
	ds_read_b128 v[200:203], v143 offset:3072
	ds_read_b128 v[204:207], v136
	ds_read_b128 v[212:215], v136 offset:1024
	ds_read_b128 v[216:219], v136 offset:2048
	ds_read_b128 v[220:223], v136 offset:3072
	ds_read_b128 v[16:19], v142 offset:32768
	ds_read_b128 v[28:31], v142 offset:33792
	ds_read_b128 v[60:63], v142 offset:34816
	ds_read_b128 v[224:227], v142 offset:35840
	ds_read_b128 v[228:231], v142 offset:36864
	ds_read_b128 v[232:235], v142 offset:37888
	ds_read_b128 v[236:239], v142 offset:38912
	ds_read_b128 v[240:243], v142 offset:39936
	s_waitcnt vmcnt(8)
	s_waitcnt lgkmcnt(0)
	s_barrier
	s_waitcnt lgkmcnt(0)
	v_mfma_f32_16x16x32_bf16 v[64:67], v[12:15], v[16:19], v[64:67]
	v_mfma_f32_16x16x32_bf16 v[124:127], v[20:23], v[28:31], v[64:67]
	v_mfma_f32_16x16x32_bf16 v[64:67], v[24:27], v[16:19], v[68:71]
	v_mfma_f32_16x16x32_bf16 v[112:115], v[200:203], v[28:31], v[64:67]
	v_mfma_f32_16x16x32_bf16 v[64:67], v[12:15], v[60:63], v[72:75]
	v_mfma_f32_16x16x32_bf16 v[108:111], v[20:23], v[224:227], v[64:67]
	v_mfma_f32_16x16x32_bf16 v[64:67], v[24:27], v[60:63], v[76:79]
	v_mfma_f32_16x16x32_bf16 v[96:99], v[200:203], v[224:227], v[64:67]
	v_mfma_f32_16x16x32_bf16 v[64:67], v[12:15], v[228:231], v[80:83]
	v_mfma_f32_16x16x32_bf16 v[92:95], v[20:23], v[232:235], v[64:67]
	v_mfma_f32_16x16x32_bf16 v[64:67], v[24:27], v[228:231], v[84:87]
	v_mfma_f32_16x16x32_bf16 v[80:83], v[200:203], v[232:235], v[64:67]
	v_mfma_f32_16x16x32_bf16 v[64:67], v[12:15], v[236:239], v[88:91]
	v_mfma_f32_16x16x32_bf16 v[76:79], v[20:23], v[240:243], v[64:67]
	v_mfma_f32_16x16x32_bf16 v[64:67], v[24:27], v[236:239], v[100:103]
	v_mfma_f32_16x16x32_bf16 v[64:67], v[200:203], v[240:243], v[64:67]
	v_mfma_f32_16x16x32_bf16 v[68:71], v[204:207], v[16:19], v[104:107]
	v_mfma_f32_16x16x32_bf16 v[16:19], v[216:219], v[16:19], v[32:35]
	v_mfma_f32_16x16x32_bf16 v[116:119], v[220:223], v[28:31], v[16:19]
	v_mfma_f32_16x16x32_bf16 v[16:19], v[204:207], v[60:63], v[36:39]
	v_mfma_f32_16x16x32_bf16 v[104:107], v[212:215], v[224:227], v[16:19]
	v_mfma_f32_16x16x32_bf16 v[16:19], v[216:219], v[60:63], v[40:43]
	v_mfma_f32_16x16x32_bf16 v[100:103], v[220:223], v[224:227], v[16:19]
	v_mfma_f32_16x16x32_bf16 v[16:19], v[204:207], v[228:231], v[44:47]
	v_mfma_f32_16x16x32_bf16 v[88:91], v[212:215], v[232:235], v[16:19]
	v_mfma_f32_16x16x32_bf16 v[16:19], v[216:219], v[228:231], v[48:51]
	v_mfma_f32_16x16x32_bf16 v[84:87], v[220:223], v[232:235], v[16:19]
	v_mfma_f32_16x16x32_bf16 v[16:19], v[204:207], v[236:239], v[52:55]
	v_mfma_f32_16x16x32_bf16 v[72:75], v[212:215], v[240:243], v[16:19]
	v_mfma_f32_16x16x32_bf16 v[16:19], v[216:219], v[236:239], v[56:59]
	v_mfma_f32_16x16x32_bf16 v[120:123], v[212:215], v[28:31], v[68:71]
	v_mfma_f32_16x16x32_bf16 v[68:71], v[220:223], v[240:243], v[16:19]
	s_barrier
	s_add_i32 s69, s65, s45
	s_nop 2
	v_lshl_add_u64 v[16:17], v[208:209], 0, s[10:11]
	s_mov_b32 m0, s69
	s_add_i32 s70, s69, 0x2000
	global_load_lds_dwordx4 v[16:17], off
	v_lshl_add_u64 v[16:17], v[208:209], 0, s[12:13]
	s_mov_b32 m0, s70
	s_add_i32 s71, s71, s45
	global_load_lds_dwordx4 v[16:17], off
	v_lshl_add_u64 v[16:17], v[208:209], 0, s[14:15]
	s_mov_b32 m0, s71
	s_add_i32 s72, s71, 0x2000
	global_load_lds_dwordx4 v[16:17], off
	v_lshl_add_u64 v[16:17], v[208:209], 0, s[16:17]
	s_mov_b32 m0, s72
	s_nop 0
	global_load_lds_dwordx4 v[16:17], off
	v_lshl_add_u64 v[16:17], v[248:249], 0, s[10:11]
	s_mov_b32 m0, s53
	s_nop 0
	global_load_lds_dwordx4 v[16:17], off
	v_lshl_add_u64 v[16:17], v[248:249], 0, s[12:13]
	s_mov_b32 m0, s54
	s_nop 0
	global_load_lds_dwordx4 v[16:17], off
	ds_read_b128 v[36:39], v142 offset:49152
	ds_read_b128 v[40:43], v142 offset:50176
	ds_read_b128 v[224:227], v142 offset:51200
	ds_read_b128 v[228:231], v142 offset:52224
	ds_read_b128 v[232:235], v142 offset:53248
	ds_read_b128 v[236:239], v142 offset:54272
	ds_read_b128 v[240:243], v142 offset:55296
	ds_read_b128 v[244:247], v142 offset:56320
	s_waitcnt vmcnt(8)
	s_waitcnt lgkmcnt(0)
	s_barrier
	s_waitcnt lgkmcnt(0)
	v_mfma_f32_16x16x32_bf16 v[16:19], v[12:15], v[36:39], v[144:147]
	v_mfma_f32_16x16x32_bf16 v[60:63], v[20:23], v[40:43], v[16:19]
	v_mfma_f32_16x16x32_bf16 v[16:19], v[24:27], v[36:39], v[148:151]
	v_mfma_f32_16x16x32_bf16 v[48:51], v[200:203], v[40:43], v[16:19]
	v_mfma_f32_16x16x32_bf16 v[16:19], v[12:15], v[224:227], v[152:155]
	v_mfma_f32_16x16x32_bf16 v[44:47], v[20:23], v[228:231], v[16:19]
	v_mfma_f32_16x16x32_bf16 v[16:19], v[24:27], v[224:227], v[156:159]
	v_mfma_f32_16x16x32_bf16 v[32:35], v[200:203], v[228:231], v[16:19]
	v_mfma_f32_16x16x32_bf16 v[16:19], v[12:15], v[232:235], v[160:163]
	v_mfma_f32_16x16x32_bf16 v[0:3], v[12:15], v[240:243], v[0:3]
	v_mfma_f32_16x16x32_bf16 v[28:31], v[20:23], v[236:239], v[16:19]
	v_mfma_f32_16x16x32_bf16 v[16:19], v[24:27], v[232:235], v[164:167]
	v_mfma_f32_16x16x32_bf16 v[12:15], v[20:23], v[244:247], v[0:3]
	v_mfma_f32_16x16x32_bf16 v[0:3], v[24:27], v[240:243], v[4:7]
	v_mfma_f32_16x16x32_bf16 v[16:19], v[200:203], v[236:239], v[16:19]
	v_mfma_f32_16x16x32_bf16 v[0:3], v[200:203], v[244:247], v[0:3]
	v_mfma_f32_16x16x32_bf16 v[4:7], v[204:207], v[36:39], v[8:11]
	v_mfma_f32_16x16x32_bf16 v[56:59], v[212:215], v[40:43], v[4:7]
	v_mfma_f32_16x16x32_bf16 v[4:7], v[216:219], v[36:39], v[172:175]
	v_mfma_f32_16x16x32_bf16 v[52:55], v[220:223], v[40:43], v[4:7]
	v_mfma_f32_16x16x32_bf16 v[4:7], v[204:207], v[224:227], v[176:179]
	v_mfma_f32_16x16x32_bf16 v[40:43], v[212:215], v[228:231], v[4:7]
	v_mfma_f32_16x16x32_bf16 v[4:7], v[216:219], v[224:227], v[180:183]
	v_mfma_f32_16x16x32_bf16 v[36:39], v[220:223], v[228:231], v[4:7]
	v_mfma_f32_16x16x32_bf16 v[4:7], v[204:207], v[232:235], v[184:187]
	v_mfma_f32_16x16x32_bf16 v[24:27], v[212:215], v[236:239], v[4:7]
	v_mfma_f32_16x16x32_bf16 v[4:7], v[216:219], v[232:235], v[188:191]
	v_mfma_f32_16x16x32_bf16 v[20:23], v[220:223], v[236:239], v[4:7]
	v_mfma_f32_16x16x32_bf16 v[4:7], v[204:207], v[240:243], v[192:195]
	v_mfma_f32_16x16x32_bf16 v[8:11], v[212:215], v[244:247], v[4:7]
	v_mfma_f32_16x16x32_bf16 v[4:7], v[216:219], v[240:243], v[196:199]
	v_mfma_f32_16x16x32_bf16 v[4:7], v[220:223], v[244:247], v[4:7]
	s_barrier
.LBB0_970:
	s_add_i32 s21, s21, 2
	s_xor_b32 s38, s21, s100
	s_ashr_i32 s39, s38, 31
	s_lshl_b64 s[74:75], s[38:39], 7
	s_add_i32 s39, s74, s99
	s_mov_b32 s73, 0
	s_add_u32 s76, s34, s39
	s_addc_u32 s77, s35, s73
	s_add_u32 s78, s30, s39
	s_addc_u32 s73, s31, s73
	s_cmp_eq_u32 s21, 14
	s_cselect_b32 s39, s67, s77
	s_cselect_b32 s38, s68, s76
	s_cselect_b32 s77, s23, s73
	s_cselect_b32 s76, s66, s78
	s_add_u32 s74, s34, s74
	s_addc_u32 s75, s35, s75
	v_lshl_add_u64 v[208:209], s[74:75], 0, v[130:131]
	s_mov_b32 m0, s59
	v_lshl_add_u64 v[216:217], v[208:209], 0, s[14:15]
	global_load_lds_dwordx4 v[216:217], off
	v_lshl_add_u64 v[208:209], v[208:209], 0, s[16:17]
	s_mov_b32 m0, s60
	s_nop 0
	global_load_lds_dwordx4 v[208:209], off
	ds_read_b128 v[144:147], v140
	ds_read_b128 v[148:151], v140 offset:1024
	ds_read_b128 v[152:155], v140 offset:2048
	ds_read_b128 v[156:159], v140 offset:3072
	ds_read_b128 v[160:163], v141
	ds_read_b128 v[164:167], v141 offset:1024
	ds_read_b128 v[172:175], v141 offset:2048
	ds_read_b128 v[176:179], v141 offset:3072
	ds_read_b128 v[180:183], v142
	ds_read_b128 v[184:187], v142 offset:1024
	ds_read_b128 v[188:191], v142 offset:2048
	ds_read_b128 v[192:195], v142 offset:3072
	ds_read_b128 v[196:199], v142 offset:4096
	ds_read_b128 v[200:203], v142 offset:5120
	ds_read_b128 v[204:207], v142 offset:6144
	ds_read_b128 v[212:215], v142 offset:7168
	s_waitcnt vmcnt(8)
	s_waitcnt lgkmcnt(0)
	s_barrier
	s_waitcnt lgkmcnt(0)
	v_mfma_f32_16x16x32_bf16 v[124:127], v[144:147], v[180:183], v[124:127]
	v_mfma_f32_16x16x32_bf16 v[124:127], v[148:151], v[184:187], v[124:127]
	v_mfma_f32_16x16x32_bf16 v[112:115], v[156:159], v[184:187], v[112:115]
	v_mfma_f32_16x16x32_bf16 v[112:115], v[152:155], v[180:183], v[112:115]
	v_mfma_f32_16x16x32_bf16 v[120:123], v[160:163], v[180:183], v[120:123]
	v_mfma_f32_16x16x32_bf16 v[120:123], v[164:167], v[184:187], v[120:123]
	v_mfma_f32_16x16x32_bf16 v[116:119], v[176:179], v[184:187], v[116:119]
	v_mfma_f32_16x16x32_bf16 v[116:119], v[172:175], v[180:183], v[116:119]
	v_mfma_f32_16x16x32_bf16 v[100:103], v[172:175], v[188:191], v[100:103]
	v_mfma_f32_16x16x32_bf16 v[100:103], v[176:179], v[192:195], v[100:103]
	v_mfma_f32_16x16x32_bf16 v[104:107], v[164:167], v[192:195], v[104:107]
	v_mfma_f32_16x16x32_bf16 v[104:107], v[160:163], v[188:191], v[104:107]
	v_mfma_f32_16x16x32_bf16 v[96:99], v[152:155], v[188:191], v[96:99]
	v_mfma_f32_16x16x32_bf16 v[96:99], v[156:159], v[192:195], v[96:99]
	v_mfma_f32_16x16x32_bf16 v[108:111], v[148:151], v[192:195], v[108:111]
	v_mfma_f32_16x16x32_bf16 v[108:111], v[144:147], v[188:191], v[108:111]
	v_mfma_f32_16x16x32_bf16 v[92:95], v[144:147], v[196:199], v[92:95]
	v_mfma_f32_16x16x32_bf16 v[92:95], v[148:151], v[200:203], v[92:95]
	v_mfma_f32_16x16x32_bf16 v[80:83], v[156:159], v[200:203], v[80:83]
	v_mfma_f32_16x16x32_bf16 v[80:83], v[152:155], v[196:199], v[80:83]
	v_mfma_f32_16x16x32_bf16 v[88:91], v[160:163], v[196:199], v[88:91]
	v_mfma_f32_16x16x32_bf16 v[88:91], v[164:167], v[200:203], v[88:91]
	v_mfma_f32_16x16x32_bf16 v[84:87], v[176:179], v[200:203], v[84:87]
	v_mfma_f32_16x16x32_bf16 v[84:87], v[172:175], v[196:199], v[84:87]
	v_mfma_f32_16x16x32_bf16 v[68:71], v[172:175], v[204:207], v[68:71]
	v_mfma_f32_16x16x32_bf16 v[68:71], v[176:179], v[212:215], v[68:71]
	v_mfma_f32_16x16x32_bf16 v[72:75], v[164:167], v[212:215], v[72:75]
	v_mfma_f32_16x16x32_bf16 v[72:75], v[160:163], v[204:207], v[72:75]
	v_mfma_f32_16x16x32_bf16 v[64:67], v[152:155], v[204:207], v[64:67]
	v_mfma_f32_16x16x32_bf16 v[64:67], v[156:159], v[212:215], v[64:67]
	v_mfma_f32_16x16x32_bf16 v[76:79], v[148:151], v[212:215], v[76:79]
	v_mfma_f32_16x16x32_bf16 v[76:79], v[144:147], v[204:207], v[76:79]
	s_barrier
	s_mov_b32 m0, s61
	v_lshl_add_u64 v[208:209], s[76:77], 0, v[128:129]
	global_load_lds_dwordx4 v[208:209], off
	v_lshl_add_u64 v[216:217], v[208:209], 0, s[0:1]
	s_mov_b32 m0, s62
	s_nop 0
	global_load_lds_dwordx4 v[216:217], off
	v_lshl_add_u64 v[216:217], v[208:209], 0, s[2:3]
	s_mov_b32 m0, s63
	s_nop 0
	global_load_lds_dwordx4 v[216:217], off
	v_lshl_add_u64 v[216:217], v[208:209], 0, s[4:5]
	s_mov_b32 m0, s64
	s_nop 0
	global_load_lds_dwordx4 v[216:217], off
	v_lshl_add_u64 v[216:217], s[38:39], 0, v[130:131]
	s_mov_b32 m0, s48
	v_lshl_add_u64 v[218:219], v[216:217], 0, s[0:1]
	global_load_lds_dwordx4 v[216:217], off
	s_mov_b32 m0, s49
	s_nop 0
	global_load_lds_dwordx4 v[218:219], off
	ds_read_b128 v[180:183], v142 offset:16384
	ds_read_b128 v[184:187], v142 offset:17408
	ds_read_b128 v[188:191], v142 offset:18432
	ds_read_b128 v[192:195], v142 offset:19456
	ds_read_b128 v[196:199], v142 offset:20480
	ds_read_b128 v[200:203], v142 offset:21504
	ds_read_b128 v[204:207], v142 offset:22528
	ds_read_b128 v[212:215], v142 offset:23552
	s_waitcnt vmcnt(8)
	s_waitcnt lgkmcnt(0)
	s_barrier
	s_waitcnt lgkmcnt(0)
	v_mfma_f32_16x16x32_bf16 v[60:63], v[144:147], v[180:183], v[60:63]
	v_mfma_f32_16x16x32_bf16 v[60:63], v[148:151], v[184:187], v[60:63]
	v_mfma_f32_16x16x32_bf16 v[48:51], v[156:159], v[184:187], v[48:51]
	v_mfma_f32_16x16x32_bf16 v[48:51], v[152:155], v[180:183], v[48:51]
	v_mfma_f32_16x16x32_bf16 v[56:59], v[160:163], v[180:183], v[56:59]
	v_mfma_f32_16x16x32_bf16 v[56:59], v[164:167], v[184:187], v[56:59]
	v_mfma_f32_16x16x32_bf16 v[52:55], v[176:179], v[184:187], v[52:55]
	v_mfma_f32_16x16x32_bf16 v[52:55], v[172:175], v[180:183], v[52:55]
	v_mfma_f32_16x16x32_bf16 v[36:39], v[172:175], v[188:191], v[36:39]
	v_mfma_f32_16x16x32_bf16 v[36:39], v[176:179], v[192:195], v[36:39]
	v_mfma_f32_16x16x32_bf16 v[40:43], v[164:167], v[192:195], v[40:43]
	v_mfma_f32_16x16x32_bf16 v[40:43], v[160:163], v[188:191], v[40:43]
	v_mfma_f32_16x16x32_bf16 v[32:35], v[152:155], v[188:191], v[32:35]
	v_mfma_f32_16x16x32_bf16 v[32:35], v[156:159], v[192:195], v[32:35]
	v_mfma_f32_16x16x32_bf16 v[44:47], v[148:151], v[192:195], v[44:47]
	v_mfma_f32_16x16x32_bf16 v[44:47], v[144:147], v[188:191], v[44:47]
	v_mfma_f32_16x16x32_bf16 v[28:31], v[144:147], v[196:199], v[28:31]
	v_mfma_f32_16x16x32_bf16 v[28:31], v[148:151], v[200:203], v[28:31]
	v_mfma_f32_16x16x32_bf16 v[16:19], v[156:159], v[200:203], v[16:19]
	v_mfma_f32_16x16x32_bf16 v[16:19], v[152:155], v[196:199], v[16:19]
	v_mfma_f32_16x16x32_bf16 v[24:27], v[160:163], v[196:199], v[24:27]
	v_mfma_f32_16x16x32_bf16 v[24:27], v[164:167], v[200:203], v[24:27]
	v_mfma_f32_16x16x32_bf16 v[20:23], v[176:179], v[200:203], v[20:23]
	v_mfma_f32_16x16x32_bf16 v[20:23], v[172:175], v[196:199], v[20:23]
	v_mfma_f32_16x16x32_bf16 v[4:7], v[172:175], v[204:207], v[4:7]
	v_mfma_f32_16x16x32_bf16 v[4:7], v[176:179], v[212:215], v[4:7]
	v_mfma_f32_16x16x32_bf16 v[8:11], v[164:167], v[212:215], v[8:11]
	v_mfma_f32_16x16x32_bf16 v[8:11], v[160:163], v[204:207], v[8:11]
	v_mfma_f32_16x16x32_bf16 v[0:3], v[152:155], v[204:207], v[0:3]
	v_mfma_f32_16x16x32_bf16 v[0:3], v[156:159], v[212:215], v[0:3]
	v_mfma_f32_16x16x32_bf16 v[12:15], v[148:151], v[212:215], v[12:15]
	v_mfma_f32_16x16x32_bf16 v[12:15], v[144:147], v[204:207], v[12:15]
	s_barrier
	s_mov_b32 m0, s50
	v_lshl_add_u64 v[218:219], v[216:217], 0, s[2:3]
	global_load_lds_dwordx4 v[218:219], off
	v_lshl_add_u64 v[218:219], v[216:217], 0, s[4:5]
	s_mov_b32 m0, s51
	s_nop 0
	global_load_lds_dwordx4 v[218:219], off
	ds_read_b128 v[144:147], v143
	ds_read_b128 v[148:151], v143 offset:1024
	ds_read_b128 v[152:155], v143 offset:2048
	ds_read_b128 v[156:159], v143 offset:3072
	ds_read_b128 v[160:163], v136
	ds_read_b128 v[164:167], v136 offset:1024
	ds_read_b128 v[172:175], v136 offset:2048
	ds_read_b128 v[176:179], v136 offset:3072
	ds_read_b128 v[180:183], v142 offset:32768
	ds_read_b128 v[184:187], v142 offset:33792
	ds_read_b128 v[188:191], v142 offset:34816
	ds_read_b128 v[192:195], v142 offset:35840
	ds_read_b128 v[196:199], v142 offset:36864
	ds_read_b128 v[200:203], v142 offset:37888
	ds_read_b128 v[204:207], v142 offset:38912
	ds_read_b128 v[212:215], v142 offset:39936
	s_waitcnt vmcnt(8)
	s_waitcnt lgkmcnt(0)
	s_barrier
	s_waitcnt lgkmcnt(0)
	v_mfma_f32_16x16x32_bf16 v[124:127], v[144:147], v[180:183], v[124:127]
	v_mfma_f32_16x16x32_bf16 v[124:127], v[148:151], v[184:187], v[124:127]
	v_mfma_f32_16x16x32_bf16 v[112:115], v[156:159], v[184:187], v[112:115]
	v_mfma_f32_16x16x32_bf16 v[112:115], v[152:155], v[180:183], v[112:115]
	v_mfma_f32_16x16x32_bf16 v[120:123], v[160:163], v[180:183], v[120:123]
	v_mfma_f32_16x16x32_bf16 v[120:123], v[164:167], v[184:187], v[120:123]
	v_mfma_f32_16x16x32_bf16 v[116:119], v[176:179], v[184:187], v[116:119]
	v_mfma_f32_16x16x32_bf16 v[116:119], v[172:175], v[180:183], v[116:119]
	v_mfma_f32_16x16x32_bf16 v[100:103], v[172:175], v[188:191], v[100:103]
	v_mfma_f32_16x16x32_bf16 v[100:103], v[176:179], v[192:195], v[100:103]
	v_mfma_f32_16x16x32_bf16 v[104:107], v[164:167], v[192:195], v[104:107]
	v_mfma_f32_16x16x32_bf16 v[104:107], v[160:163], v[188:191], v[104:107]
	v_mfma_f32_16x16x32_bf16 v[96:99], v[152:155], v[188:191], v[96:99]
	v_mfma_f32_16x16x32_bf16 v[96:99], v[156:159], v[192:195], v[96:99]
	v_mfma_f32_16x16x32_bf16 v[108:111], v[148:151], v[192:195], v[108:111]
	v_mfma_f32_16x16x32_bf16 v[108:111], v[144:147], v[188:191], v[108:111]
	v_mfma_f32_16x16x32_bf16 v[92:95], v[144:147], v[196:199], v[92:95]
	v_mfma_f32_16x16x32_bf16 v[92:95], v[148:151], v[200:203], v[92:95]
	v_mfma_f32_16x16x32_bf16 v[80:83], v[156:159], v[200:203], v[80:83]
	v_mfma_f32_16x16x32_bf16 v[80:83], v[152:155], v[196:199], v[80:83]
	v_mfma_f32_16x16x32_bf16 v[88:91], v[160:163], v[196:199], v[88:91]
	v_mfma_f32_16x16x32_bf16 v[88:91], v[164:167], v[200:203], v[88:91]
	v_mfma_f32_16x16x32_bf16 v[84:87], v[176:179], v[200:203], v[84:87]
	v_mfma_f32_16x16x32_bf16 v[84:87], v[172:175], v[196:199], v[84:87]
	v_mfma_f32_16x16x32_bf16 v[68:71], v[172:175], v[204:207], v[68:71]
	v_mfma_f32_16x16x32_bf16 v[68:71], v[176:179], v[212:215], v[68:71]
	v_mfma_f32_16x16x32_bf16 v[72:75], v[164:167], v[212:215], v[72:75]
	v_mfma_f32_16x16x32_bf16 v[72:75], v[160:163], v[204:207], v[72:75]
	v_mfma_f32_16x16x32_bf16 v[64:67], v[152:155], v[204:207], v[64:67]
	v_mfma_f32_16x16x32_bf16 v[64:67], v[156:159], v[212:215], v[64:67]
	v_mfma_f32_16x16x32_bf16 v[76:79], v[148:151], v[212:215], v[76:79]
	v_mfma_f32_16x16x32_bf16 v[76:79], v[144:147], v[204:207], v[76:79]
	s_barrier
	s_mov_b32 m0, s69
	v_lshl_add_u64 v[218:219], v[208:209], 0, s[10:11]
	global_load_lds_dwordx4 v[218:219], off
	v_lshl_add_u64 v[218:219], v[208:209], 0, s[12:13]
	s_mov_b32 m0, s70
	s_nop 0
	global_load_lds_dwordx4 v[218:219], off
	v_lshl_add_u64 v[218:219], v[208:209], 0, s[14:15]
	s_mov_b32 m0, s71
	v_lshl_add_u64 v[208:209], v[208:209], 0, s[16:17]
	global_load_lds_dwordx4 v[218:219], off
	s_mov_b32 m0, s72
	s_nop 0
	global_load_lds_dwordx4 v[208:209], off
	v_lshl_add_u64 v[208:209], v[216:217], 0, s[10:11]
	s_mov_b32 m0, s53
	s_nop 0
	global_load_lds_dwordx4 v[208:209], off
	v_lshl_add_u64 v[208:209], v[216:217], 0, s[12:13]
	s_mov_b32 m0, s54
	s_nop 0
	global_load_lds_dwordx4 v[208:209], off
	ds_read_b128 v[180:183], v142 offset:49152
	ds_read_b128 v[184:187], v142 offset:50176
	ds_read_b128 v[188:191], v142 offset:51200
	ds_read_b128 v[192:195], v142 offset:52224
	ds_read_b128 v[196:199], v142 offset:53248
	ds_read_b128 v[200:203], v142 offset:54272
	ds_read_b128 v[204:207], v142 offset:55296
	ds_read_b128 v[212:215], v142 offset:56320
	s_waitcnt vmcnt(8)
	s_waitcnt lgkmcnt(0)
	s_barrier
	s_waitcnt lgkmcnt(0)
	v_mfma_f32_16x16x32_bf16 v[60:63], v[144:147], v[180:183], v[60:63]
	v_mfma_f32_16x16x32_bf16 v[60:63], v[148:151], v[184:187], v[60:63]
	v_mfma_f32_16x16x32_bf16 v[48:51], v[156:159], v[184:187], v[48:51]
	v_mfma_f32_16x16x32_bf16 v[48:51], v[152:155], v[180:183], v[48:51]
	v_mfma_f32_16x16x32_bf16 v[56:59], v[160:163], v[180:183], v[56:59]
	v_mfma_f32_16x16x32_bf16 v[56:59], v[164:167], v[184:187], v[56:59]
	v_mfma_f32_16x16x32_bf16 v[52:55], v[176:179], v[184:187], v[52:55]
	v_mfma_f32_16x16x32_bf16 v[52:55], v[172:175], v[180:183], v[52:55]
	v_mfma_f32_16x16x32_bf16 v[36:39], v[172:175], v[188:191], v[36:39]
	v_mfma_f32_16x16x32_bf16 v[36:39], v[176:179], v[192:195], v[36:39]
	v_mfma_f32_16x16x32_bf16 v[40:43], v[164:167], v[192:195], v[40:43]
	v_mfma_f32_16x16x32_bf16 v[40:43], v[160:163], v[188:191], v[40:43]
	v_mfma_f32_16x16x32_bf16 v[32:35], v[152:155], v[188:191], v[32:35]
	v_mfma_f32_16x16x32_bf16 v[32:35], v[156:159], v[192:195], v[32:35]
	v_mfma_f32_16x16x32_bf16 v[44:47], v[148:151], v[192:195], v[44:47]
	v_mfma_f32_16x16x32_bf16 v[44:47], v[144:147], v[188:191], v[44:47]
	v_mfma_f32_16x16x32_bf16 v[28:31], v[144:147], v[196:199], v[28:31]
	v_mfma_f32_16x16x32_bf16 v[28:31], v[148:151], v[200:203], v[28:31]
	v_mfma_f32_16x16x32_bf16 v[16:19], v[156:159], v[200:203], v[16:19]
	v_mfma_f32_16x16x32_bf16 v[16:19], v[152:155], v[196:199], v[16:19]
	v_mfma_f32_16x16x32_bf16 v[24:27], v[160:163], v[196:199], v[24:27]
	v_mfma_f32_16x16x32_bf16 v[24:27], v[164:167], v[200:203], v[24:27]
	v_mfma_f32_16x16x32_bf16 v[20:23], v[176:179], v[200:203], v[20:23]
	v_mfma_f32_16x16x32_bf16 v[20:23], v[172:175], v[196:199], v[20:23]
	v_mfma_f32_16x16x32_bf16 v[4:7], v[172:175], v[204:207], v[4:7]
	v_mfma_f32_16x16x32_bf16 v[4:7], v[176:179], v[212:215], v[4:7]
	v_mfma_f32_16x16x32_bf16 v[8:11], v[164:167], v[212:215], v[8:11]
	v_mfma_f32_16x16x32_bf16 v[8:11], v[160:163], v[204:207], v[8:11]
	v_mfma_f32_16x16x32_bf16 v[0:3], v[152:155], v[204:207], v[0:3]
	v_mfma_f32_16x16x32_bf16 v[0:3], v[156:159], v[212:215], v[0:3]
	v_mfma_f32_16x16x32_bf16 v[12:15], v[148:151], v[212:215], v[12:15]
	v_mfma_f32_16x16x32_bf16 v[12:15], v[144:147], v[204:207], v[12:15]
	s_barrier
	s_cmp_gt_u32 s21, 13
	s_cbranch_scc0 .LBB0_970
	s_and_b64 vcc, exec, s[18:19]
	s_cbranch_vccz .LBB0_973
	s_barrier

	.amdhsa_kernel _Z14fwd_megakernel4Args
		.amdhsa_group_segment_fixed_size 0
		.amdhsa_private_segment_fixed_size 0
		.amdhsa_kernarg_size 408
		.amdhsa_user_sgpr_count 2
		.amdhsa_user_sgpr_dispatch_ptr 0
		.amdhsa_user_sgpr_queue_ptr 0
		.amdhsa_user_sgpr_kernarg_segment_ptr 1
		.amdhsa_user_sgpr_dispatch_id 0
		.amdhsa_user_sgpr_kernarg_preload_length 0
		.amdhsa_user_sgpr_kernarg_preload_offset 0
		.amdhsa_user_sgpr_private_segment_size 0
		.amdhsa_uses_dynamic_stack 0
		.amdhsa_enable_private_segment 0
		.amdhsa_system_sgpr_workgroup_id_x 1
		.amdhsa_system_sgpr_workgroup_id_y 0
		.amdhsa_system_sgpr_workgroup_id_z 0
		.amdhsa_system_sgpr_workgroup_info 0
		.amdhsa_system_vgpr_workitem_id 2
		.amdhsa_next_free_vgpr 253
		.amdhsa_next_free_sgpr 102
		.amdhsa_accum_offset 256
		.amdhsa_reserve_vcc 1
		.amdhsa_float_round_mode_32 0
		.amdhsa_float_round_mode_16_64 0
		.amdhsa_float_denorm_mode_32 3
		.amdhsa_float_denorm_mode_16_64 3
		.amdhsa_dx10_clamp 1
		.amdhsa_ieee_mode 1
		.amdhsa_fp16_overflow 0
		.amdhsa_tg_split 0
		.amdhsa_exception_fp_ieee_invalid_op 0
		.amdhsa_exception_fp_denorm_src 0
		.amdhsa_exception_fp_ieee_div_zero 0
		.amdhsa_exception_fp_ieee_overflow 0
		.amdhsa_exception_fp_ieee_underflow 0
		.amdhsa_exception_fp_ieee_inexact 0
		.amdhsa_exception_int_div_zero 0
	.end_amdhsa_kernel

amdhsa.kernels:
  - .agpr_count:     0
    .args:
      - .offset:         0
        .size:           152
        .value_kind:     by_value
      - .offset:         152
        .size:           4
        .value_kind:     hidden_block_count_x
      - .offset:         156
        .size:           4
        .value_kind:     hidden_block_count_y
      - .offset:         160
        .size:           4
        .value_kind:     hidden_block_count_z
      - .offset:         164
        .size:           2
        .value_kind:     hidden_group_size_x
      - .offset:         166
        .size:           2
        .value_kind:     hidden_group_size_y
      - .offset:         168
        .size:           2
        .value_kind:     hidden_group_size_z
      - .offset:         170
        .size:           2
        .value_kind:     hidden_remainder_x
      - .offset:         172
        .size:           2
        .value_kind:     hidden_remainder_y
      - .offset:         174
        .size:           2
        .value_kind:     hidden_remainder_z
      - .offset:         192
        .size:           8
        .value_kind:     hidden_global_offset_x
      - .offset:         200
        .size:           8
        .value_kind:     hidden_global_offset_y
      - .offset:         208
        .size:           8
        .value_kind:     hidden_global_offset_z
      - .offset:         216
        .size:           2
        .value_kind:     hidden_grid_dims
      - .offset:         240
        .size:           8
        .value_kind:     hidden_multigrid_sync_arg
      - .offset:         272
        .size:           4
        .value_kind:     hidden_dynamic_lds_size
    .group_segment_fixed_size: 0
    .kernarg_segment_align: 8
    .kernarg_segment_size: 408
    .language:       OpenCL C
    .language_version:
      - 2
      - 0
    .max_flat_workgroup_size: 512
    .name:           _Z14fwd_megakernel4Args
    .private_segment_fixed_size: 0
    .sgpr_count:     108
    .sgpr_spill_count: 136
    .symbol:         _Z14fwd_megakernel4Args.kd
    .uniform_work_group_size: 1
    .uses_dynamic_stack: false
    .vgpr_count:     253
    .vgpr_spill_count: 0
    .wavefront_size: 64
